# v46 + GEMM MFMA blocks cleaned: removed the five already-satisfied s_waitcnt lgkmcnt and the mid-block s_setprio 0/1 pair from every 32-MFMA block (lgkmcnt(0) precedes the block's barrier)
# baseline (speedup 1.0000x reference)
; #define PG8_STAGE(bufoff, gbase, voff) do { _Pragma("unroll") for (int _i = 0; _i < 2; ++_i) \
;         pg8_glds((const void*)(gbase), (voff)[_i], (unsigned)__builtin_amdgcn_readfirstlane((int)(lds_u + (unsigned)(bufoff) + ldsw + (unsigned)(_i * 8192)))); } while (0)
; #define PG8_LDA(dst, b, h) do { _Pragma("unroll") for (int m = 0; m < 4; ++m) _Pragma("unroll") for (int k = 0; k < 2; ++k) dst[m][k] = *(const PG8_LAS bf16x8*)(lds + PG8_SA(b, h) + aoff + m * 2048 + k * 1024); } while (0)
; #define PG8_LDB(dst, b, h) do { _Pragma("unroll") for (int n = 0; n < 2; ++n) _Pragma("unroll") for (int k = 0; k < 2; ++k) dst[n][k] = *(const PG8_LAS bf16x8*)(lds + PG8_SB(b, h) + boff + n * 2048 + k * 1024); } while (0)
; #define PG8_MMA(ai, bj, At, Bt) do { __builtin_amdgcn_s_setprio(1); _Pragma("unroll") for (int m = 0; m < 4; ++m) _Pragma("unroll") for (int n = 0; n < 2; ++n) _Pragma("unroll") for (int k = 0; k < 2; ++k) \
;         acc[ai][bj][m][n] = __builtin_amdgcn_mfma_f32_16x16x32_bf16(Bt[n][k], At[m][k], acc[ai][bj][m][n], 0, 0, 0); __builtin_amdgcn_s_setprio(0); } while (0)
; #define PG8_WAIT_V(n) asm volatile("s_waitcnt vmcnt(" #n ")" ::: "memory")
; #define PG8_WAIT_L(n) asm volatile("s_waitcnt lgkmcnt(" #n ")" ::: "memory")
; #define PG8_BAR __builtin_amdgcn_s_barrier()
; #define PG8_SCHED __builtin_amdgcn_sched_barrier(0)
; template <class Epi, class Sched, bool ALIGN_EPI = false, bool SP2 = false>
; __device__ __forceinline__ void gemm_phase(PG8_LAS unsigned char* lds, const Gemm g, const Sched& S, const Epi& E) {
;     ...
;             PG8_LDB(B0, 0, 0); PG8_LDB(B1, 0, 1); PG8_SCHED; PG8_LDA(At, 0, 0); PG8_STAGE(PG8_SA(1, 1), a1 + hstepA, voffA);
;             PG8_WAIT_V(8); PG8_WAIT_L(0); PG8_BAR; PG8_MMA(0, 0, At, B0); PG8_MMA(0, 1, At, B1); PG8_BAR; PG8_SCHED;
;             PG8_LDA(At, 0, 1); PG8_STAGE(PG8_SB(0, 0), b2, voffB); PG8_STAGE(PG8_SB(0, 1), b2 + hstepB, voffB); PG8_STAGE(PG8_SA(0, 0), a2, voffA);
;             PG8_WAIT_V(8); PG8_WAIT_L(0); PG8_BAR; PG8_MMA(1, 0, At, B0); PG8_MMA(1, 1, At, B1); PG8_BAR; PG8_SCHED;
.LBB0_75:
	ds_read_b128 v[148:151], v137
	ds_read_b128 v[152:155], v137 offset:1024
	ds_read_b128 v[156:159], v137 offset:2048
	ds_read_b128 v[160:163], v137 offset:3072
	ds_read_b128 v[164:167], v138
	ds_read_b128 v[168:171], v138 offset:1024
	ds_read_b128 v[172:175], v138 offset:2048
	ds_read_b128 v[176:179], v138 offset:3072
	s_add_i32 s19, s18, 2
	s_cmp_eq_u32 s67, s18
	s_cselect_b32 s52, s42, s37
	s_cselect_b32 s53, s43, s39
	s_cselect_b32 s50, s44, s70
	s_cselect_b32 s51, s45, s71
	s_add_u32 s48, s52, 0x80
	s_addc_u32 s49, s53, 0
	ds_read_b128 v[180:183], v139
	ds_read_b128 v[184:187], v139 offset:1024
	ds_read_b128 v[188:191], v139 offset:2048
	ds_read_b128 v[192:195], v139 offset:3072
	ds_read_b128 v[196:199], v139 offset:4096
	ds_read_b128 v[200:203], v139 offset:5120
	ds_read_b128 v[204:207], v139 offset:6144
	ds_read_b128 v[208:211], v139 offset:7168
	v_readfirstlane_b32 s18, v140
	s_mov_b32 m0, s18
	s_nop 0
	global_load_lds_dwordx4 v130, s[46:47]
	v_readfirstlane_b32 s18, v141
	s_add_i32 s18, s18, 0
	s_add_i32 s18, s18, 0xe000
	s_mov_b32 m0, s18
	s_nop 0
	global_load_lds_dwordx4 v132, s[46:47]
	s_waitcnt vmcnt(8)
	s_waitcnt lgkmcnt(0)
	s_barrier
	s_setprio 1
	v_mfma_f32_16x16x32_bf16 v[120:123], v[148:151], v[180:183], v[120:123]
	v_mfma_f32_16x16x32_bf16 v[124:127], v[156:159], v[180:183], v[124:127]
	v_mfma_f32_16x16x32_bf16 v[108:111], v[148:151], v[188:191], v[108:111]
	v_mfma_f32_16x16x32_bf16 v[104:107], v[156:159], v[188:191], v[104:107]
	v_mfma_f32_16x16x32_bf16 v[92:95], v[148:151], v[196:199], v[92:95]
	v_mfma_f32_16x16x32_bf16 v[88:91], v[156:159], v[196:199], v[88:91]
	v_mfma_f32_16x16x32_bf16 v[76:79], v[148:151], v[204:207], v[76:79]
	v_mfma_f32_16x16x32_bf16 v[72:75], v[156:159], v[204:207], v[72:75]
	v_mfma_f32_16x16x32_bf16 v[120:123], v[152:155], v[184:187], v[120:123]
	v_mfma_f32_16x16x32_bf16 v[124:127], v[160:163], v[184:187], v[124:127]
	v_mfma_f32_16x16x32_bf16 v[108:111], v[152:155], v[192:195], v[108:111]
	v_mfma_f32_16x16x32_bf16 v[104:107], v[160:163], v[192:195], v[104:107]
	v_mfma_f32_16x16x32_bf16 v[92:95], v[152:155], v[200:203], v[92:95]
	v_mfma_f32_16x16x32_bf16 v[88:91], v[160:163], v[200:203], v[88:91]
	v_mfma_f32_16x16x32_bf16 v[76:79], v[152:155], v[208:211], v[76:79]
	v_mfma_f32_16x16x32_bf16 v[72:75], v[160:163], v[208:211], v[72:75]
	v_mfma_f32_16x16x32_bf16 v[116:119], v[164:167], v[180:183], v[116:119]
	v_mfma_f32_16x16x32_bf16 v[112:115], v[172:175], v[180:183], v[112:115]
	v_mfma_f32_16x16x32_bf16 v[100:103], v[164:167], v[188:191], v[100:103]
	v_mfma_f32_16x16x32_bf16 v[96:99], v[172:175], v[188:191], v[96:99]
	v_mfma_f32_16x16x32_bf16 v[84:87], v[164:167], v[196:199], v[84:87]
	v_mfma_f32_16x16x32_bf16 v[80:83], v[172:175], v[196:199], v[80:83]
	v_mfma_f32_16x16x32_bf16 v[68:71], v[164:167], v[204:207], v[68:71]
	v_mfma_f32_16x16x32_bf16 v[64:67], v[172:175], v[204:207], v[64:67]
	v_mfma_f32_16x16x32_bf16 v[116:119], v[168:171], v[184:187], v[116:119]
	v_mfma_f32_16x16x32_bf16 v[112:115], v[176:179], v[184:187], v[112:115]
	v_mfma_f32_16x16x32_bf16 v[100:103], v[168:171], v[192:195], v[100:103]
	v_mfma_f32_16x16x32_bf16 v[96:99], v[176:179], v[192:195], v[96:99]
	v_mfma_f32_16x16x32_bf16 v[84:87], v[168:171], v[200:203], v[84:87]
	v_mfma_f32_16x16x32_bf16 v[80:83], v[176:179], v[200:203], v[80:83]
	v_mfma_f32_16x16x32_bf16 v[68:71], v[168:171], v[208:211], v[68:71]
	v_mfma_f32_16x16x32_bf16 v[64:67], v[176:179], v[208:211], v[64:67]
	s_setprio 0
	s_barrier
	ds_read_b128 v[180:183], v139 offset:16384
	ds_read_b128 v[184:187], v139 offset:17408
	ds_read_b128 v[188:191], v139 offset:18432
	ds_read_b128 v[192:195], v139 offset:19456
	ds_read_b128 v[196:199], v139 offset:20480
	ds_read_b128 v[200:203], v139 offset:21504
	ds_read_b128 v[204:207], v139 offset:22528
	ds_read_b128 v[208:211], v139 offset:23552
	v_readfirstlane_b32 s18, v142
	s_mov_b32 m0, s18
	s_nop 0
	global_load_lds_dwordx4 v131, s[50:51]
	v_readfirstlane_b32 s18, v143
	s_mov_b32 m0, s18
	s_nop 0
	global_load_lds_dwordx4 v133, s[50:51]
	s_add_u32 s72, s50, s24
	s_addc_u32 s73, s51, s25
	v_readfirstlane_b32 s18, v144
	s_mov_b32 m0, s18
	s_nop 0
	global_load_lds_dwordx4 v131, s[72:73]
	v_readfirstlane_b32 s18, v145
	s_mov_b32 m0, s18
	s_nop 0
	global_load_lds_dwordx4 v133, s[72:73]
	v_readfirstlane_b32 s18, v146
	s_mov_b32 m0, s18
	s_nop 0
	global_load_lds_dwordx4 v130, s[52:53]
	s_nop 0
	s_mov_b32 m0, s41
	s_nop 0
	global_load_lds_dwordx4 v132, s[52:53]
	s_waitcnt vmcnt(8)
	s_waitcnt lgkmcnt(0)
	s_barrier
	s_setprio 1
	v_mfma_f32_16x16x32_bf16 v[60:63], v[148:151], v[180:183], v[60:63]
	v_mfma_f32_16x16x32_bf16 v[56:59], v[156:159], v[180:183], v[56:59]
	v_mfma_f32_16x16x32_bf16 v[44:47], v[148:151], v[188:191], v[44:47]
	v_mfma_f32_16x16x32_bf16 v[40:43], v[156:159], v[188:191], v[40:43]
	v_mfma_f32_16x16x32_bf16 v[28:31], v[148:151], v[196:199], v[28:31]
	v_mfma_f32_16x16x32_bf16 v[24:27], v[156:159], v[196:199], v[24:27]
	v_mfma_f32_16x16x32_bf16 v[12:15], v[148:151], v[204:207], v[12:15]
	v_mfma_f32_16x16x32_bf16 v[8:11], v[156:159], v[204:207], v[8:11]
	v_mfma_f32_16x16x32_bf16 v[60:63], v[152:155], v[184:187], v[60:63]
	v_mfma_f32_16x16x32_bf16 v[56:59], v[160:163], v[184:187], v[56:59]
	v_mfma_f32_16x16x32_bf16 v[44:47], v[152:155], v[192:195], v[44:47]
	v_mfma_f32_16x16x32_bf16 v[40:43], v[160:163], v[192:195], v[40:43]
	v_mfma_f32_16x16x32_bf16 v[28:31], v[152:155], v[200:203], v[28:31]
	v_mfma_f32_16x16x32_bf16 v[24:27], v[160:163], v[200:203], v[24:27]
	v_mfma_f32_16x16x32_bf16 v[12:15], v[152:155], v[208:211], v[12:15]
	v_mfma_f32_16x16x32_bf16 v[8:11], v[160:163], v[208:211], v[8:11]
	v_mfma_f32_16x16x32_bf16 v[52:55], v[164:167], v[180:183], v[52:55]
	v_mfma_f32_16x16x32_bf16 v[48:51], v[172:175], v[180:183], v[48:51]
	v_mfma_f32_16x16x32_bf16 v[36:39], v[164:167], v[188:191], v[36:39]
	v_mfma_f32_16x16x32_bf16 v[32:35], v[172:175], v[188:191], v[32:35]
	v_mfma_f32_16x16x32_bf16 v[20:23], v[164:167], v[196:199], v[20:23]
	v_mfma_f32_16x16x32_bf16 v[16:19], v[172:175], v[196:199], v[16:19]
	v_mfma_f32_16x16x32_bf16 v[4:7], v[164:167], v[204:207], v[4:7]
	v_mfma_f32_16x16x32_bf16 v[0:3], v[172:175], v[204:207], v[0:3]
	v_mfma_f32_16x16x32_bf16 v[52:55], v[168:171], v[184:187], v[52:55]
	v_mfma_f32_16x16x32_bf16 v[48:51], v[176:179], v[184:187], v[48:51]
	v_mfma_f32_16x16x32_bf16 v[36:39], v[168:171], v[192:195], v[36:39]
	v_mfma_f32_16x16x32_bf16 v[32:35], v[176:179], v[192:195], v[32:35]
	v_mfma_f32_16x16x32_bf16 v[20:23], v[168:171], v[200:203], v[20:23]
	v_mfma_f32_16x16x32_bf16 v[16:19], v[176:179], v[200:203], v[16:19]
	v_mfma_f32_16x16x32_bf16 v[4:7], v[168:171], v[208:211], v[4:7]
	v_mfma_f32_16x16x32_bf16 v[0:3], v[176:179], v[208:211], v[0:3]
	s_setprio 0
	s_barrier
; #define PG8_STAGE(bufoff, gbase, voff) do { _Pragma("unroll") for (int _i = 0; _i < 2; ++_i) \
;         pg8_glds((const void*)(gbase), (voff)[_i], (unsigned)__builtin_amdgcn_readfirstlane((int)(lds_u + (unsigned)(bufoff) + ldsw + (unsigned)(_i * 8192)))); } while (0)
; #define PG8_LDA(dst, b, h) do { _Pragma("unroll") for (int m = 0; m < 4; ++m) _Pragma("unroll") for (int k = 0; k < 2; ++k) dst[m][k] = *(const PG8_LAS bf16x8*)(lds + PG8_SA(b, h) + aoff + m * 2048 + k * 1024); } while (0)
; #define PG8_LDB(dst, b, h) do { _Pragma("unroll") for (int n = 0; n < 2; ++n) _Pragma("unroll") for (int k = 0; k < 2; ++k) dst[n][k] = *(const PG8_LAS bf16x8*)(lds + PG8_SB(b, h) + boff + n * 2048 + k * 1024); } while (0)
; #define PG8_MMA(ai, bj, At, Bt) do { __builtin_amdgcn_s_setprio(1); _Pragma("unroll") for (int m = 0; m < 4; ++m) _Pragma("unroll") for (int n = 0; n < 2; ++n) _Pragma("unroll") for (int k = 0; k < 2; ++k) \
;         acc[ai][bj][m][n] = __builtin_amdgcn_mfma_f32_16x16x32_bf16(Bt[n][k], At[m][k], acc[ai][bj][m][n], 0, 0, 0); __builtin_amdgcn_s_setprio(0); } while (0)
; #define PG8_WAIT_V(n) asm volatile("s_waitcnt vmcnt(" #n ")" ::: "memory")
; #define PG8_WAIT_L(n) asm volatile("s_waitcnt lgkmcnt(" #n ")" ::: "memory")
; #define PG8_BAR __builtin_amdgcn_s_barrier()
; #define PG8_SCHED __builtin_amdgcn_sched_barrier(0)
; template <class Epi, class Sched, bool ALIGN_EPI = false, bool SP2 = false>
; __device__ __forceinline__ void gemm_phase(PG8_LAS unsigned char* lds, const Gemm g, const Sched& S, const Epi& E) {
;     ...
;             PG8_LDB(B0, 1, 0); PG8_LDB(B1, 1, 1); PG8_SCHED; PG8_LDA(At, 1, 0); PG8_STAGE(PG8_SA(0, 1), a2 + hstepA, voffA);
;             PG8_WAIT_V(8); PG8_WAIT_L(0); PG8_BAR; PG8_MMA(0, 0, At, B0); PG8_MMA(0, 1, At, B1); PG8_BAR; PG8_SCHED;
;             PG8_LDA(At, 1, 1); PG8_STAGE(PG8_SB(1, 0), b3, voffB); PG8_STAGE(PG8_SB(1, 1), b3 + hstepB, voffB); PG8_STAGE(PG8_SA(1, 0), a3, voffA);
;             PG8_WAIT_V(8); PG8_WAIT_L(0); PG8_BAR; PG8_MMA(1, 0, At, B0); PG8_MMA(1, 1, At, B1); PG8_BAR; PG8_SCHED;
	v_add_u32_e32 v147, 0x18000, v136
	ds_read_b128 v[148:151], v147
	ds_read_b128 v[152:155], v147 offset:1024
	ds_read_b128 v[156:159], v147 offset:2048
	ds_read_b128 v[160:163], v147 offset:3072
	v_add_u32_e32 v147, 0x1c000, v136
	ds_read_b128 v[164:167], v147
	ds_read_b128 v[168:171], v147 offset:1024
	ds_read_b128 v[172:175], v147 offset:2048
	ds_read_b128 v[176:179], v147 offset:3072
	ds_read_b128 v[180:183], v139 offset:32768
	ds_read_b128 v[184:187], v139 offset:33792
	ds_read_b128 v[188:191], v139 offset:34816
	ds_read_b128 v[192:195], v139 offset:35840
	ds_read_b128 v[196:199], v139 offset:36864
	ds_read_b128 v[200:203], v139 offset:37888
	ds_read_b128 v[204:207], v139 offset:38912
	ds_read_b128 v[208:211], v139 offset:39936
	s_add_u32 s52, s52, 0x80000
	s_addc_u32 s53, s53, 0
	s_mov_b32 m0, s58
	s_nop 0
	global_load_lds_dwordx4 v130, s[52:53]
	s_nop 0
	s_mov_b32 m0, s59
	s_nop 0
	global_load_lds_dwordx4 v132, s[52:53]
	s_waitcnt vmcnt(8)
	s_waitcnt lgkmcnt(0)
	s_barrier
	s_setprio 1
	v_mfma_f32_16x16x32_bf16 v[120:123], v[148:151], v[180:183], v[120:123]
	v_mfma_f32_16x16x32_bf16 v[124:127], v[156:159], v[180:183], v[124:127]
	v_mfma_f32_16x16x32_bf16 v[108:111], v[148:151], v[188:191], v[108:111]
	v_mfma_f32_16x16x32_bf16 v[104:107], v[156:159], v[188:191], v[104:107]
	v_mfma_f32_16x16x32_bf16 v[92:95], v[148:151], v[196:199], v[92:95]
	v_mfma_f32_16x16x32_bf16 v[88:91], v[156:159], v[196:199], v[88:91]
	v_mfma_f32_16x16x32_bf16 v[76:79], v[148:151], v[204:207], v[76:79]
	v_mfma_f32_16x16x32_bf16 v[72:75], v[156:159], v[204:207], v[72:75]
	v_mfma_f32_16x16x32_bf16 v[120:123], v[152:155], v[184:187], v[120:123]
	v_mfma_f32_16x16x32_bf16 v[124:127], v[160:163], v[184:187], v[124:127]
	v_mfma_f32_16x16x32_bf16 v[108:111], v[152:155], v[192:195], v[108:111]
	v_mfma_f32_16x16x32_bf16 v[104:107], v[160:163], v[192:195], v[104:107]
	v_mfma_f32_16x16x32_bf16 v[92:95], v[152:155], v[200:203], v[92:95]
	v_mfma_f32_16x16x32_bf16 v[88:91], v[160:163], v[200:203], v[88:91]
	v_mfma_f32_16x16x32_bf16 v[76:79], v[152:155], v[208:211], v[76:79]
	v_mfma_f32_16x16x32_bf16 v[72:75], v[160:163], v[208:211], v[72:75]
	v_mfma_f32_16x16x32_bf16 v[116:119], v[164:167], v[180:183], v[116:119]
	v_mfma_f32_16x16x32_bf16 v[112:115], v[172:175], v[180:183], v[112:115]
	v_mfma_f32_16x16x32_bf16 v[100:103], v[164:167], v[188:191], v[100:103]
	v_mfma_f32_16x16x32_bf16 v[96:99], v[172:175], v[188:191], v[96:99]
	v_mfma_f32_16x16x32_bf16 v[84:87], v[164:167], v[196:199], v[84:87]
	v_mfma_f32_16x16x32_bf16 v[80:83], v[172:175], v[196:199], v[80:83]
	v_mfma_f32_16x16x32_bf16 v[68:71], v[164:167], v[204:207], v[68:71]
	v_mfma_f32_16x16x32_bf16 v[64:67], v[172:175], v[204:207], v[64:67]
	v_mfma_f32_16x16x32_bf16 v[116:119], v[168:171], v[184:187], v[116:119]
	v_mfma_f32_16x16x32_bf16 v[112:115], v[176:179], v[184:187], v[112:115]
	v_mfma_f32_16x16x32_bf16 v[100:103], v[168:171], v[192:195], v[100:103]
	v_mfma_f32_16x16x32_bf16 v[96:99], v[176:179], v[192:195], v[96:99]
	v_mfma_f32_16x16x32_bf16 v[84:87], v[168:171], v[200:203], v[84:87]
	v_mfma_f32_16x16x32_bf16 v[80:83], v[176:179], v[200:203], v[80:83]
	v_mfma_f32_16x16x32_bf16 v[68:71], v[168:171], v[208:211], v[68:71]
	v_mfma_f32_16x16x32_bf16 v[64:67], v[176:179], v[208:211], v[64:67]
	s_setprio 0
	s_barrier
	ds_read_b128 v[180:183], v139 offset:49152
	ds_read_b128 v[184:187], v139 offset:50176
	ds_read_b128 v[188:191], v139 offset:51200
	ds_read_b128 v[192:195], v139 offset:52224
	ds_read_b128 v[196:199], v139 offset:53248
	ds_read_b128 v[200:203], v139 offset:54272
	ds_read_b128 v[204:207], v139 offset:55296
	ds_read_b128 v[208:211], v139 offset:56320
	s_add_u32 s50, s50, 0x80
	s_addc_u32 s51, s51, 0
	s_mov_b32 m0, s61
	s_nop 0
	global_load_lds_dwordx4 v131, s[50:51]
	s_nop 0
	s_mov_b32 m0, s62
	s_nop 0
	global_load_lds_dwordx4 v133, s[50:51]
	s_add_u32 s50, s50, s24
	s_addc_u32 s51, s51, s25
	s_mov_b32 m0, s65
	s_nop 0
	global_load_lds_dwordx4 v131, s[50:51]
	s_nop 0
	s_mov_b32 m0, s66
	s_nop 0
	global_load_lds_dwordx4 v133, s[50:51]
	s_nop 0
	s_mov_b32 m0, s63
	s_nop 0
	global_load_lds_dwordx4 v130, s[48:49]
	s_nop 0
	s_mov_b32 m0, s64
	s_nop 0
	global_load_lds_dwordx4 v132, s[48:49]
	s_waitcnt vmcnt(8)
	s_waitcnt lgkmcnt(0)
	s_barrier
	s_setprio 1
	v_mfma_f32_16x16x32_bf16 v[60:63], v[148:151], v[180:183], v[60:63]
	v_mfma_f32_16x16x32_bf16 v[56:59], v[156:159], v[180:183], v[56:59]
	v_mfma_f32_16x16x32_bf16 v[44:47], v[148:151], v[188:191], v[44:47]
	v_mfma_f32_16x16x32_bf16 v[40:43], v[156:159], v[188:191], v[40:43]
	v_mfma_f32_16x16x32_bf16 v[28:31], v[148:151], v[196:199], v[28:31]
	v_mfma_f32_16x16x32_bf16 v[24:27], v[156:159], v[196:199], v[24:27]
	v_mfma_f32_16x16x32_bf16 v[12:15], v[148:151], v[204:207], v[12:15]
	v_mfma_f32_16x16x32_bf16 v[8:11], v[156:159], v[204:207], v[8:11]
	v_mfma_f32_16x16x32_bf16 v[60:63], v[152:155], v[184:187], v[60:63]
	v_mfma_f32_16x16x32_bf16 v[56:59], v[160:163], v[184:187], v[56:59]
	v_mfma_f32_16x16x32_bf16 v[44:47], v[152:155], v[192:195], v[44:47]
	v_mfma_f32_16x16x32_bf16 v[40:43], v[160:163], v[192:195], v[40:43]
	v_mfma_f32_16x16x32_bf16 v[28:31], v[152:155], v[200:203], v[28:31]
	v_mfma_f32_16x16x32_bf16 v[24:27], v[160:163], v[200:203], v[24:27]
	v_mfma_f32_16x16x32_bf16 v[12:15], v[152:155], v[208:211], v[12:15]
	v_mfma_f32_16x16x32_bf16 v[8:11], v[160:163], v[208:211], v[8:11]
	v_mfma_f32_16x16x32_bf16 v[52:55], v[164:167], v[180:183], v[52:55]
	v_mfma_f32_16x16x32_bf16 v[48:51], v[172:175], v[180:183], v[48:51]
	v_mfma_f32_16x16x32_bf16 v[36:39], v[164:167], v[188:191], v[36:39]
	v_mfma_f32_16x16x32_bf16 v[32:35], v[172:175], v[188:191], v[32:35]
	v_mfma_f32_16x16x32_bf16 v[20:23], v[164:167], v[196:199], v[20:23]
	v_mfma_f32_16x16x32_bf16 v[16:19], v[172:175], v[196:199], v[16:19]
	v_mfma_f32_16x16x32_bf16 v[4:7], v[164:167], v[204:207], v[4:7]
	v_mfma_f32_16x16x32_bf16 v[0:3], v[172:175], v[204:207], v[0:3]
	v_mfma_f32_16x16x32_bf16 v[52:55], v[168:171], v[184:187], v[52:55]
	v_mfma_f32_16x16x32_bf16 v[48:51], v[176:179], v[184:187], v[48:51]
	v_mfma_f32_16x16x32_bf16 v[36:39], v[168:171], v[192:195], v[36:39]
	v_mfma_f32_16x16x32_bf16 v[32:35], v[176:179], v[192:195], v[32:35]
	v_mfma_f32_16x16x32_bf16 v[20:23], v[168:171], v[200:203], v[20:23]
	v_mfma_f32_16x16x32_bf16 v[16:19], v[176:179], v[200:203], v[16:19]
	v_mfma_f32_16x16x32_bf16 v[4:7], v[168:171], v[208:211], v[4:7]
	v_mfma_f32_16x16x32_bf16 v[0:3], v[176:179], v[208:211], v[0:3]
	s_setprio 0
	s_barrier
	s_add_u32 s37, s37, 0x100
	s_addc_u32 s39, s39, 0
	s_add_u32 s70, s70, 0x100
	s_addc_u32 s71, s71, 0
	s_add_u32 s46, s46, 0x100
	s_addc_u32 s47, s47, 0
	s_cmp_ge_i32 s19, s60
	s_mov_b32 s18, s19
	s_cbranch_scc0 .LBB0_75

; #define PG8_STAGE(bufoff, gbase, voff) do { _Pragma("unroll") for (int _i = 0; _i < 2; ++_i) \
;         pg8_glds((const void*)(gbase), (voff)[_i], (unsigned)__builtin_amdgcn_readfirstlane((int)(lds_u + (unsigned)(bufoff) + ldsw + (unsigned)(_i * 8192)))); } while (0)
; #define PG8_LDA(dst, b, h) do { _Pragma("unroll") for (int m = 0; m < 4; ++m) _Pragma("unroll") for (int k = 0; k < 2; ++k) dst[m][k] = *(const PG8_LAS bf16x8*)(lds + PG8_SA(b, h) + aoff + m * 2048 + k * 1024); } while (0)
; #define PG8_LDB(dst, b, h) do { _Pragma("unroll") for (int n = 0; n < 2; ++n) _Pragma("unroll") for (int k = 0; k < 2; ++k) dst[n][k] = *(const PG8_LAS bf16x8*)(lds + PG8_SB(b, h) + boff + n * 2048 + k * 1024); } while (0)
; #define PG8_MMA(ai, bj, At, Bt) do { __builtin_amdgcn_s_setprio(1); _Pragma("unroll") for (int m = 0; m < 4; ++m) _Pragma("unroll") for (int n = 0; n < 2; ++n) _Pragma("unroll") for (int k = 0; k < 2; ++k) \
;         acc[ai][bj][m][n] = __builtin_amdgcn_mfma_f32_16x16x32_bf16(Bt[n][k], At[m][k], acc[ai][bj][m][n], 0, 0, 0); __builtin_amdgcn_s_setprio(0); } while (0)
; #define PG8_WAIT_V(n) asm volatile("s_waitcnt vmcnt(" #n ")" ::: "memory")
; #define PG8_WAIT_L(n) asm volatile("s_waitcnt lgkmcnt(" #n ")" ::: "memory")
; #define PG8_BAR __builtin_amdgcn_s_barrier()
; #define PG8_SCHED __builtin_amdgcn_sched_barrier(0)
; template <class Epi, class Sched, bool ALIGN_EPI = false, bool SP2 = false>
; __device__ __forceinline__ void gemm_phase(PG8_LAS unsigned char* lds, const Gemm g, const Sched& S, const Epi& E) {
;     ...
;             PG8_LDB(B0, 0, 0); PG8_LDB(B1, 0, 1); PG8_SCHED; PG8_LDA(At, 0, 0); PG8_STAGE(PG8_SA(1, 1), a1 + hstepA, voffA);
;             PG8_WAIT_V(8); PG8_WAIT_L(0); PG8_BAR; PG8_MMA(0, 0, At, B0); PG8_MMA(0, 1, At, B1); PG8_BAR; PG8_SCHED;
;             PG8_LDA(At, 0, 1); PG8_STAGE(PG8_SB(0, 0), b2, voffB); PG8_STAGE(PG8_SB(0, 1), b2 + hstepB, voffB); PG8_STAGE(PG8_SA(0, 0), a2, voffA);
;             PG8_WAIT_V(8); PG8_WAIT_L(0); PG8_BAR; PG8_MMA(1, 0, At, B0); PG8_MMA(1, 1, At, B1); PG8_BAR; PG8_SCHED;
.LBB0_156:
	ds_read_b128 v[130:133], v144
	ds_read_b128 v[134:137], v144 offset:1024
	ds_read_b128 v[150:153], v144 offset:2048
	ds_read_b128 v[154:157], v144 offset:3072
	ds_read_b128 v[158:161], v145
	ds_read_b128 v[162:165], v145 offset:1024
	ds_read_b128 v[166:169], v145 offset:2048
	ds_read_b128 v[170:173], v145 offset:3072
	s_add_u32 s64, s62, 0x100
	s_addc_u32 s65, s63, 0
	s_cmp_eq_u32 s87, 28
	s_cselect_b32 s70, s13, s64
	s_cselect_b32 s71, s9, s65
	s_cselect_b32 s68, s57, s86
	s_cselect_b32 s69, s55, s18
	s_add_u32 s66, s70, 0x80
	s_addc_u32 s67, s71, 0
	ds_read_b128 v[174:177], v146
	ds_read_b128 v[178:181], v146 offset:1024
	ds_read_b128 v[182:185], v146 offset:2048
	ds_read_b128 v[186:189], v146 offset:3072
	ds_read_b128 v[190:193], v146 offset:4096
	ds_read_b128 v[194:197], v146 offset:5120
	ds_read_b128 v[198:201], v146 offset:6144
	ds_read_b128 v[202:205], v146 offset:7168
	s_add_u32 s62, s62, 0x80080
	s_addc_u32 s63, s63, 0
	s_mov_b32 m0, s80
	s_nop 0
	global_load_lds_dwordx4 v138, s[62:63]
	s_add_i32 s88, s24, 0xe000
	s_mov_b32 m0, s88
	s_nop 0
	global_load_lds_dwordx4 v140, s[62:63]
	s_waitcnt vmcnt(8)
	s_waitcnt lgkmcnt(0)
	s_barrier
	s_setprio 1
	v_mfma_f32_16x16x32_bf16 v[126:129], v[130:133], v[174:177], v[126:129]
	v_mfma_f32_16x16x32_bf16 v[122:125], v[150:153], v[174:177], v[122:125]
	v_mfma_f32_16x16x32_bf16 v[110:113], v[130:133], v[182:185], v[110:113]
	v_mfma_f32_16x16x32_bf16 v[106:109], v[150:153], v[182:185], v[106:109]
	v_mfma_f32_16x16x32_bf16 v[94:97], v[130:133], v[190:193], v[94:97]
	v_mfma_f32_16x16x32_bf16 v[90:93], v[150:153], v[190:193], v[90:93]
	v_mfma_f32_16x16x32_bf16 v[78:81], v[130:133], v[198:201], v[78:81]
	v_mfma_f32_16x16x32_bf16 v[74:77], v[150:153], v[198:201], v[74:77]
	v_mfma_f32_16x16x32_bf16 v[126:129], v[134:137], v[178:181], v[126:129]
	v_mfma_f32_16x16x32_bf16 v[122:125], v[154:157], v[178:181], v[122:125]
	v_mfma_f32_16x16x32_bf16 v[110:113], v[134:137], v[186:189], v[110:113]
	v_mfma_f32_16x16x32_bf16 v[106:109], v[154:157], v[186:189], v[106:109]
	v_mfma_f32_16x16x32_bf16 v[94:97], v[134:137], v[194:197], v[94:97]
	v_mfma_f32_16x16x32_bf16 v[90:93], v[154:157], v[194:197], v[90:93]
	v_mfma_f32_16x16x32_bf16 v[78:81], v[134:137], v[202:205], v[78:81]
	v_mfma_f32_16x16x32_bf16 v[74:77], v[154:157], v[202:205], v[74:77]
	v_mfma_f32_16x16x32_bf16 v[118:121], v[158:161], v[174:177], v[118:121]
	v_mfma_f32_16x16x32_bf16 v[114:117], v[166:169], v[174:177], v[114:117]
	v_mfma_f32_16x16x32_bf16 v[102:105], v[158:161], v[182:185], v[102:105]
	v_mfma_f32_16x16x32_bf16 v[98:101], v[166:169], v[182:185], v[98:101]
	v_mfma_f32_16x16x32_bf16 v[86:89], v[158:161], v[190:193], v[86:89]
	v_mfma_f32_16x16x32_bf16 v[82:85], v[166:169], v[190:193], v[82:85]
	v_mfma_f32_16x16x32_bf16 v[70:73], v[158:161], v[198:201], v[70:73]
	v_mfma_f32_16x16x32_bf16 v[66:69], v[166:169], v[198:201], v[66:69]
	v_mfma_f32_16x16x32_bf16 v[118:121], v[162:165], v[178:181], v[118:121]
	v_mfma_f32_16x16x32_bf16 v[114:117], v[170:173], v[178:181], v[114:117]
	v_mfma_f32_16x16x32_bf16 v[102:105], v[162:165], v[186:189], v[102:105]
	v_mfma_f32_16x16x32_bf16 v[98:101], v[170:173], v[186:189], v[98:101]
	v_mfma_f32_16x16x32_bf16 v[86:89], v[162:165], v[194:197], v[86:89]
	v_mfma_f32_16x16x32_bf16 v[82:85], v[170:173], v[194:197], v[82:85]
	v_mfma_f32_16x16x32_bf16 v[70:73], v[162:165], v[202:205], v[70:73]
	v_mfma_f32_16x16x32_bf16 v[66:69], v[170:173], v[202:205], v[66:69]
	s_setprio 0
	s_barrier
	ds_read_b128 v[174:177], v146 offset:16384
	ds_read_b128 v[178:181], v146 offset:17408
	ds_read_b128 v[182:185], v146 offset:18432
	ds_read_b128 v[186:189], v146 offset:19456
	ds_read_b128 v[190:193], v146 offset:20480
	ds_read_b128 v[194:197], v146 offset:21504
	ds_read_b128 v[198:201], v146 offset:22528
	ds_read_b128 v[202:205], v146 offset:23552
	s_mov_b32 m0, s28
	s_nop 0
	global_load_lds_dwordx4 v139, s[68:69]
	s_add_u32 s62, s68, 0x80000
	s_mov_b32 m0, s29
	s_nop 0
	global_load_lds_dwordx4 v141, s[68:69]
	s_addc_u32 s63, s69, 0
	s_mov_b32 m0, s30
	s_nop 0
	global_load_lds_dwordx4 v139, s[62:63]
	s_nop 0
	s_mov_b32 m0, s33
	s_nop 0
	global_load_lds_dwordx4 v141, s[62:63]
	s_nop 0
	s_mov_b32 m0, s24
	s_nop 0
	global_load_lds_dwordx4 v138, s[70:71]
	s_nop 0
	s_mov_b32 m0, s43
	s_nop 0
	global_load_lds_dwordx4 v140, s[70:71]
	s_waitcnt vmcnt(8)
	s_waitcnt lgkmcnt(0)
	s_barrier
	s_setprio 1
	v_mfma_f32_16x16x32_bf16 v[62:65], v[130:133], v[174:177], v[62:65]
	v_mfma_f32_16x16x32_bf16 v[58:61], v[150:153], v[174:177], v[58:61]
	v_mfma_f32_16x16x32_bf16 v[46:49], v[130:133], v[182:185], v[46:49]
	v_mfma_f32_16x16x32_bf16 v[42:45], v[150:153], v[182:185], v[42:45]
	v_mfma_f32_16x16x32_bf16 v[30:33], v[130:133], v[190:193], v[30:33]
	v_mfma_f32_16x16x32_bf16 v[26:29], v[150:153], v[190:193], v[26:29]
	v_mfma_f32_16x16x32_bf16 v[14:17], v[130:133], v[198:201], v[14:17]
	v_mfma_f32_16x16x32_bf16 v[10:13], v[150:153], v[198:201], v[10:13]
	v_mfma_f32_16x16x32_bf16 v[62:65], v[134:137], v[178:181], v[62:65]
	v_mfma_f32_16x16x32_bf16 v[58:61], v[154:157], v[178:181], v[58:61]
	v_mfma_f32_16x16x32_bf16 v[46:49], v[134:137], v[186:189], v[46:49]
	v_mfma_f32_16x16x32_bf16 v[42:45], v[154:157], v[186:189], v[42:45]
	v_mfma_f32_16x16x32_bf16 v[30:33], v[134:137], v[194:197], v[30:33]
	v_mfma_f32_16x16x32_bf16 v[26:29], v[154:157], v[194:197], v[26:29]
	v_mfma_f32_16x16x32_bf16 v[14:17], v[134:137], v[202:205], v[14:17]
	v_mfma_f32_16x16x32_bf16 v[10:13], v[154:157], v[202:205], v[10:13]
	v_mfma_f32_16x16x32_bf16 v[54:57], v[158:161], v[174:177], v[54:57]
	v_mfma_f32_16x16x32_bf16 v[50:53], v[166:169], v[174:177], v[50:53]
	v_mfma_f32_16x16x32_bf16 v[38:41], v[158:161], v[182:185], v[38:41]
	v_mfma_f32_16x16x32_bf16 v[34:37], v[166:169], v[182:185], v[34:37]
	v_mfma_f32_16x16x32_bf16 v[22:25], v[158:161], v[190:193], v[22:25]
	v_mfma_f32_16x16x32_bf16 v[18:21], v[166:169], v[190:193], v[18:21]
	v_mfma_f32_16x16x32_bf16 v[6:9], v[158:161], v[198:201], v[6:9]
	v_mfma_f32_16x16x32_bf16 v[2:5], v[166:169], v[198:201], v[2:5]
	v_mfma_f32_16x16x32_bf16 v[54:57], v[162:165], v[178:181], v[54:57]
	v_mfma_f32_16x16x32_bf16 v[50:53], v[170:173], v[178:181], v[50:53]
	v_mfma_f32_16x16x32_bf16 v[38:41], v[162:165], v[186:189], v[38:41]
	v_mfma_f32_16x16x32_bf16 v[34:37], v[170:173], v[186:189], v[34:37]
	v_mfma_f32_16x16x32_bf16 v[22:25], v[162:165], v[194:197], v[22:25]
	v_mfma_f32_16x16x32_bf16 v[18:21], v[170:173], v[194:197], v[18:21]
	v_mfma_f32_16x16x32_bf16 v[6:9], v[162:165], v[202:205], v[6:9]
	v_mfma_f32_16x16x32_bf16 v[2:5], v[170:173], v[202:205], v[2:5]
	s_setprio 0
	s_barrier
; #define PG8_STAGE(bufoff, gbase, voff) do { _Pragma("unroll") for (int _i = 0; _i < 2; ++_i) \
;         pg8_glds((const void*)(gbase), (voff)[_i], (unsigned)__builtin_amdgcn_readfirstlane((int)(lds_u + (unsigned)(bufoff) + ldsw + (unsigned)(_i * 8192)))); } while (0)
; #define PG8_LDA(dst, b, h) do { _Pragma("unroll") for (int m = 0; m < 4; ++m) _Pragma("unroll") for (int k = 0; k < 2; ++k) dst[m][k] = *(const PG8_LAS bf16x8*)(lds + PG8_SA(b, h) + aoff + m * 2048 + k * 1024); } while (0)
; #define PG8_LDB(dst, b, h) do { _Pragma("unroll") for (int n = 0; n < 2; ++n) _Pragma("unroll") for (int k = 0; k < 2; ++k) dst[n][k] = *(const PG8_LAS bf16x8*)(lds + PG8_SB(b, h) + boff + n * 2048 + k * 1024); } while (0)
; #define PG8_MMA(ai, bj, At, Bt) do { __builtin_amdgcn_s_setprio(1); _Pragma("unroll") for (int m = 0; m < 4; ++m) _Pragma("unroll") for (int n = 0; n < 2; ++n) _Pragma("unroll") for (int k = 0; k < 2; ++k) \
;         acc[ai][bj][m][n] = __builtin_amdgcn_mfma_f32_16x16x32_bf16(Bt[n][k], At[m][k], acc[ai][bj][m][n], 0, 0, 0); __builtin_amdgcn_s_setprio(0); } while (0)
; #define PG8_WAIT_V(n) asm volatile("s_waitcnt vmcnt(" #n ")" ::: "memory")
; #define PG8_WAIT_L(n) asm volatile("s_waitcnt lgkmcnt(" #n ")" ::: "memory")
; #define PG8_BAR __builtin_amdgcn_s_barrier()
; #define PG8_SCHED __builtin_amdgcn_sched_barrier(0)
; template <class Epi, class Sched, bool ALIGN_EPI = false, bool SP2 = false>
; __device__ __forceinline__ void gemm_phase(PG8_LAS unsigned char* lds, const Gemm g, const Sched& S, const Epi& E) {
;     ...
;             PG8_LDB(B0, 1, 0); PG8_LDB(B1, 1, 1); PG8_SCHED; PG8_LDA(At, 1, 0); PG8_STAGE(PG8_SA(0, 1), a2 + hstepA, voffA);
;             PG8_WAIT_V(8); PG8_WAIT_L(0); PG8_BAR; PG8_MMA(0, 0, At, B0); PG8_MMA(0, 1, At, B1); PG8_BAR; PG8_SCHED;
;             PG8_LDA(At, 1, 1); PG8_STAGE(PG8_SB(1, 0), b3, voffB); PG8_STAGE(PG8_SB(1, 1), b3 + hstepB, voffB); PG8_STAGE(PG8_SA(1, 0), a3, voffA);
;             PG8_WAIT_V(8); PG8_WAIT_L(0); PG8_BAR; PG8_MMA(1, 0, At, B0); PG8_MMA(1, 1, At, B1); PG8_BAR; PG8_SCHED;
;     ...
;         if constexpr (ALIGN_EPI) { if (wr == 0) PG8_BAR; }
	ds_read_b128 v[130:133], v147
	ds_read_b128 v[134:137], v147 offset:1024
	ds_read_b128 v[150:153], v147 offset:2048
	ds_read_b128 v[154:157], v147 offset:3072
	ds_read_b128 v[158:161], v148
	ds_read_b128 v[162:165], v148 offset:1024
	ds_read_b128 v[166:169], v148 offset:2048
	ds_read_b128 v[170:173], v148 offset:3072
	ds_read_b128 v[174:177], v146 offset:32768
	ds_read_b128 v[178:181], v146 offset:33792
	ds_read_b128 v[182:185], v146 offset:34816
	ds_read_b128 v[186:189], v146 offset:35840
	ds_read_b128 v[190:193], v146 offset:36864
	ds_read_b128 v[194:197], v146 offset:37888
	ds_read_b128 v[198:201], v146 offset:38912
	ds_read_b128 v[202:205], v146 offset:39936
	s_add_u32 s62, s70, 0x80000
	s_addc_u32 s63, s71, 0
	s_mov_b32 m0, s50
	s_nop 0
	global_load_lds_dwordx4 v138, s[62:63]
	s_nop 0
	s_mov_b32 m0, s51
	s_nop 0
	global_load_lds_dwordx4 v140, s[62:63]
	s_waitcnt vmcnt(8)
	s_waitcnt lgkmcnt(0)
	s_barrier
	s_setprio 1
	v_mfma_f32_16x16x32_bf16 v[126:129], v[130:133], v[174:177], v[126:129]
	v_mfma_f32_16x16x32_bf16 v[122:125], v[150:153], v[174:177], v[122:125]
	v_mfma_f32_16x16x32_bf16 v[110:113], v[130:133], v[182:185], v[110:113]
	v_mfma_f32_16x16x32_bf16 v[106:109], v[150:153], v[182:185], v[106:109]
	v_mfma_f32_16x16x32_bf16 v[94:97], v[130:133], v[190:193], v[94:97]
	v_mfma_f32_16x16x32_bf16 v[90:93], v[150:153], v[190:193], v[90:93]
	v_mfma_f32_16x16x32_bf16 v[78:81], v[130:133], v[198:201], v[78:81]
	v_mfma_f32_16x16x32_bf16 v[74:77], v[150:153], v[198:201], v[74:77]
	v_mfma_f32_16x16x32_bf16 v[126:129], v[134:137], v[178:181], v[126:129]
	v_mfma_f32_16x16x32_bf16 v[122:125], v[154:157], v[178:181], v[122:125]
	v_mfma_f32_16x16x32_bf16 v[110:113], v[134:137], v[186:189], v[110:113]
	v_mfma_f32_16x16x32_bf16 v[106:109], v[154:157], v[186:189], v[106:109]
	v_mfma_f32_16x16x32_bf16 v[94:97], v[134:137], v[194:197], v[94:97]
	v_mfma_f32_16x16x32_bf16 v[90:93], v[154:157], v[194:197], v[90:93]
	v_mfma_f32_16x16x32_bf16 v[78:81], v[134:137], v[202:205], v[78:81]
	v_mfma_f32_16x16x32_bf16 v[74:77], v[154:157], v[202:205], v[74:77]
	v_mfma_f32_16x16x32_bf16 v[118:121], v[158:161], v[174:177], v[118:121]
	v_mfma_f32_16x16x32_bf16 v[114:117], v[166:169], v[174:177], v[114:117]
	v_mfma_f32_16x16x32_bf16 v[102:105], v[158:161], v[182:185], v[102:105]
	v_mfma_f32_16x16x32_bf16 v[98:101], v[166:169], v[182:185], v[98:101]
	v_mfma_f32_16x16x32_bf16 v[86:89], v[158:161], v[190:193], v[86:89]
	v_mfma_f32_16x16x32_bf16 v[82:85], v[166:169], v[190:193], v[82:85]
	v_mfma_f32_16x16x32_bf16 v[70:73], v[158:161], v[198:201], v[70:73]
	v_mfma_f32_16x16x32_bf16 v[66:69], v[166:169], v[198:201], v[66:69]
	v_mfma_f32_16x16x32_bf16 v[118:121], v[162:165], v[178:181], v[118:121]
	v_mfma_f32_16x16x32_bf16 v[114:117], v[170:173], v[178:181], v[114:117]
	v_mfma_f32_16x16x32_bf16 v[102:105], v[162:165], v[186:189], v[102:105]
	v_mfma_f32_16x16x32_bf16 v[98:101], v[170:173], v[186:189], v[98:101]
	v_mfma_f32_16x16x32_bf16 v[86:89], v[162:165], v[194:197], v[86:89]
	v_mfma_f32_16x16x32_bf16 v[82:85], v[170:173], v[194:197], v[82:85]
	v_mfma_f32_16x16x32_bf16 v[70:73], v[162:165], v[202:205], v[70:73]
	v_mfma_f32_16x16x32_bf16 v[66:69], v[170:173], v[202:205], v[66:69]
	s_setprio 0
	s_barrier
	ds_read_b128 v[174:177], v146 offset:49152
	ds_read_b128 v[178:181], v146 offset:50176
	ds_read_b128 v[182:185], v146 offset:51200
	ds_read_b128 v[186:189], v146 offset:52224
	ds_read_b128 v[190:193], v146 offset:53248
	ds_read_b128 v[194:197], v146 offset:54272
	ds_read_b128 v[198:201], v146 offset:55296
	ds_read_b128 v[202:205], v146 offset:56320
	s_add_u32 s62, s68, 0x80
	s_addc_u32 s63, s69, 0
	s_mov_b32 m0, s74
	s_nop 0
	global_load_lds_dwordx4 v139, s[62:63]
	s_nop 0
	s_mov_b32 m0, s75
	s_nop 0
	global_load_lds_dwordx4 v141, s[62:63]
	s_add_u32 s62, s68, 0x80080
	s_addc_u32 s63, s69, 0
	s_mov_b32 m0, s78
	s_nop 0
	global_load_lds_dwordx4 v139, s[62:63]
	s_nop 0
	s_mov_b32 m0, s79
	s_nop 0
	global_load_lds_dwordx4 v141, s[62:63]
	s_nop 0
	s_mov_b32 m0, s76
	s_nop 0
	global_load_lds_dwordx4 v138, s[66:67]
	s_nop 0
	s_mov_b32 m0, s77
	s_nop 0
	global_load_lds_dwordx4 v140, s[66:67]
	s_waitcnt vmcnt(8)
	s_waitcnt lgkmcnt(0)
	s_barrier
	s_setprio 1
	v_mfma_f32_16x16x32_bf16 v[62:65], v[130:133], v[174:177], v[62:65]
	v_mfma_f32_16x16x32_bf16 v[58:61], v[150:153], v[174:177], v[58:61]
	v_mfma_f32_16x16x32_bf16 v[46:49], v[130:133], v[182:185], v[46:49]
	v_mfma_f32_16x16x32_bf16 v[42:45], v[150:153], v[182:185], v[42:45]
	v_mfma_f32_16x16x32_bf16 v[30:33], v[130:133], v[190:193], v[30:33]
	v_mfma_f32_16x16x32_bf16 v[26:29], v[150:153], v[190:193], v[26:29]
	v_mfma_f32_16x16x32_bf16 v[14:17], v[130:133], v[198:201], v[14:17]
	v_mfma_f32_16x16x32_bf16 v[10:13], v[150:153], v[198:201], v[10:13]
	v_mfma_f32_16x16x32_bf16 v[62:65], v[134:137], v[178:181], v[62:65]
	v_mfma_f32_16x16x32_bf16 v[58:61], v[154:157], v[178:181], v[58:61]
	v_mfma_f32_16x16x32_bf16 v[46:49], v[134:137], v[186:189], v[46:49]
	v_mfma_f32_16x16x32_bf16 v[42:45], v[154:157], v[186:189], v[42:45]
	v_mfma_f32_16x16x32_bf16 v[30:33], v[134:137], v[194:197], v[30:33]
	v_mfma_f32_16x16x32_bf16 v[26:29], v[154:157], v[194:197], v[26:29]
	v_mfma_f32_16x16x32_bf16 v[14:17], v[134:137], v[202:205], v[14:17]
	v_mfma_f32_16x16x32_bf16 v[10:13], v[154:157], v[202:205], v[10:13]
	v_mfma_f32_16x16x32_bf16 v[54:57], v[158:161], v[174:177], v[54:57]
	v_mfma_f32_16x16x32_bf16 v[50:53], v[166:169], v[174:177], v[50:53]
	v_mfma_f32_16x16x32_bf16 v[38:41], v[158:161], v[182:185], v[38:41]
	v_mfma_f32_16x16x32_bf16 v[34:37], v[166:169], v[182:185], v[34:37]
	v_mfma_f32_16x16x32_bf16 v[22:25], v[158:161], v[190:193], v[22:25]
	v_mfma_f32_16x16x32_bf16 v[18:21], v[166:169], v[190:193], v[18:21]
	v_mfma_f32_16x16x32_bf16 v[6:9], v[158:161], v[198:201], v[6:9]
	v_mfma_f32_16x16x32_bf16 v[2:5], v[166:169], v[198:201], v[2:5]
	v_mfma_f32_16x16x32_bf16 v[54:57], v[162:165], v[178:181], v[54:57]
	v_mfma_f32_16x16x32_bf16 v[50:53], v[170:173], v[178:181], v[50:53]
	v_mfma_f32_16x16x32_bf16 v[38:41], v[162:165], v[186:189], v[38:41]
	v_mfma_f32_16x16x32_bf16 v[34:37], v[170:173], v[186:189], v[34:37]
	v_mfma_f32_16x16x32_bf16 v[22:25], v[162:165], v[194:197], v[22:25]
	v_mfma_f32_16x16x32_bf16 v[18:21], v[170:173], v[194:197], v[18:21]
	v_mfma_f32_16x16x32_bf16 v[6:9], v[162:165], v[202:205], v[6:9]
	v_mfma_f32_16x16x32_bf16 v[2:5], v[170:173], v[202:205], v[2:5]
	s_setprio 0
	s_barrier
	s_add_i32 s87, s87, 2
	s_add_u32 s86, s86, 0x100
	s_addc_u32 s18, s18, 0
	s_cmp_gt_u32 s87, 29
	s_mov_b64 s[62:63], s[64:65]
	s_cbranch_scc0 .LBB0_156
	s_and_b64 vcc, exec, s[16:17]
	s_cbranch_vccz .LBB0_159
	s_barrier

; #define PG8_STAGE(bufoff, gbase, voff) do { _Pragma("unroll") for (int _i = 0; _i < 2; ++_i) \
;         pg8_glds((const void*)(gbase), (voff)[_i], (unsigned)__builtin_amdgcn_readfirstlane((int)(lds_u + (unsigned)(bufoff) + ldsw + (unsigned)(_i * 8192)))); } while (0)
; #define PG8_LDA(dst, b, h) do { _Pragma("unroll") for (int m = 0; m < 4; ++m) _Pragma("unroll") for (int k = 0; k < 2; ++k) dst[m][k] = *(const PG8_LAS bf16x8*)(lds + PG8_SA(b, h) + aoff + m * 2048 + k * 1024); } while (0)
; #define PG8_LDB(dst, b, h) do { _Pragma("unroll") for (int n = 0; n < 2; ++n) _Pragma("unroll") for (int k = 0; k < 2; ++k) dst[n][k] = *(const PG8_LAS bf16x8*)(lds + PG8_SB(b, h) + boff + n * 2048 + k * 1024); } while (0)
; #define PG8_MMA(ai, bj, At, Bt) do { __builtin_amdgcn_s_setprio(1); _Pragma("unroll") for (int m = 0; m < 4; ++m) _Pragma("unroll") for (int n = 0; n < 2; ++n) _Pragma("unroll") for (int k = 0; k < 2; ++k) \
;         acc[ai][bj][m][n] = __builtin_amdgcn_mfma_f32_16x16x32_bf16(Bt[n][k], At[m][k], acc[ai][bj][m][n], 0, 0, 0); __builtin_amdgcn_s_setprio(0); } while (0)
; #define PG8_WAIT_V(n) asm volatile("s_waitcnt vmcnt(" #n ")" ::: "memory")
; #define PG8_WAIT_L(n) asm volatile("s_waitcnt lgkmcnt(" #n ")" ::: "memory")
; #define PG8_BAR __builtin_amdgcn_s_barrier()
; #define PG8_SCHED __builtin_amdgcn_sched_barrier(0)
; template <class Epi, class Sched, bool ALIGN_EPI = false, bool SP2 = false>
; __device__ __forceinline__ void gemm_phase(PG8_LAS unsigned char* lds, const Gemm g, const Sched& S, const Epi& E) {
;     ...
;             PG8_LDB(B0, 0, 0); PG8_LDB(B1, 0, 1); PG8_SCHED; PG8_LDA(At, 0, 0); PG8_STAGE(PG8_SA(1, 1), a1 + hstepA, voffA);
;             PG8_WAIT_V(8); PG8_WAIT_L(0); PG8_BAR; PG8_MMA(0, 0, At, B0); PG8_MMA(0, 1, At, B1); PG8_BAR; PG8_SCHED;
;             PG8_LDA(At, 0, 1); PG8_STAGE(PG8_SB(0, 0), b2, voffB); PG8_STAGE(PG8_SB(0, 1), b2 + hstepB, voffB); PG8_STAGE(PG8_SA(0, 0), a2, voffA);
;             PG8_WAIT_V(8); PG8_WAIT_L(0); PG8_BAR; PG8_MMA(1, 0, At, B0); PG8_MMA(1, 1, At, B1); PG8_BAR; PG8_SCHED;
.LBB0_507:
	v_add_u32_e32 v130, 0x10000, v137
	ds_read_b128 v[140:143], v130
	ds_read_b128 v[144:147], v130 offset:1024
	ds_read_b128 v[148:151], v130 offset:2048
	ds_read_b128 v[152:155], v130 offset:3072
	v_add_u32_e32 v130, 0x14000, v137
	ds_read_b128 v[156:159], v130
	ds_read_b128 v[160:163], v130 offset:1024
	ds_read_b128 v[164:167], v130 offset:2048
	ds_read_b128 v[168:171], v130 offset:3072
	s_cmp_eq_u32 s81, 28
	s_cselect_b32 s66, s75, s77
	s_cselect_b32 s67, s17, s78
	s_cselect_b32 s64, s76, s79
	s_cselect_b32 s65, s13, s80
	s_add_u32 s62, s66, 0x80
	s_addc_u32 s63, s67, 0
	ds_read_b128 v[172:175], v138
	ds_read_b128 v[176:179], v138 offset:1024
	ds_read_b128 v[180:183], v138 offset:2048
	ds_read_b128 v[184:187], v138 offset:3072
	ds_read_b128 v[188:191], v138 offset:4096
	ds_read_b128 v[192:195], v138 offset:5120
	ds_read_b128 v[196:199], v138 offset:6144
	ds_read_b128 v[200:203], v138 offset:7168
	s_mov_b32 m0, s72
	s_nop 0
	global_load_lds_dwordx4 v1, s[60:61]
	s_add_i32 s18, s28, 0xe000
	s_mov_b32 m0, s18
	s_nop 0
	global_load_lds_dwordx4 v133, s[60:61]
	s_waitcnt vmcnt(8)
	s_waitcnt lgkmcnt(0)
	s_barrier
	s_setprio 1
	v_mfma_f32_16x16x32_bf16 v[126:129], v[140:143], v[172:175], v[126:129]
	v_mfma_f32_16x16x32_bf16 v[122:125], v[148:151], v[172:175], v[122:125]
	v_mfma_f32_16x16x32_bf16 v[118:121], v[140:143], v[180:183], v[118:121]
	v_mfma_f32_16x16x32_bf16 v[110:113], v[148:151], v[180:183], v[110:113]
	v_mfma_f32_16x16x32_bf16 v[102:105], v[140:143], v[188:191], v[102:105]
	v_mfma_f32_16x16x32_bf16 v[94:97], v[148:151], v[188:191], v[94:97]
	v_mfma_f32_16x16x32_bf16 v[86:89], v[140:143], v[196:199], v[86:89]
	v_mfma_f32_16x16x32_bf16 v[78:81], v[148:151], v[196:199], v[78:81]
	v_mfma_f32_16x16x32_bf16 v[126:129], v[144:147], v[176:179], v[126:129]
	v_mfma_f32_16x16x32_bf16 v[122:125], v[152:155], v[176:179], v[122:125]
	v_mfma_f32_16x16x32_bf16 v[118:121], v[144:147], v[184:187], v[118:121]
	v_mfma_f32_16x16x32_bf16 v[110:113], v[152:155], v[184:187], v[110:113]
	v_mfma_f32_16x16x32_bf16 v[102:105], v[144:147], v[192:195], v[102:105]
	v_mfma_f32_16x16x32_bf16 v[94:97], v[152:155], v[192:195], v[94:97]
	v_mfma_f32_16x16x32_bf16 v[86:89], v[144:147], v[200:203], v[86:89]
	v_mfma_f32_16x16x32_bf16 v[78:81], v[152:155], v[200:203], v[78:81]
	v_mfma_f32_16x16x32_bf16 v[114:117], v[156:159], v[172:175], v[114:117]
	v_mfma_f32_16x16x32_bf16 v[106:109], v[164:167], v[172:175], v[106:109]
	v_mfma_f32_16x16x32_bf16 v[98:101], v[156:159], v[180:183], v[98:101]
	v_mfma_f32_16x16x32_bf16 v[90:93], v[164:167], v[180:183], v[90:93]
	v_mfma_f32_16x16x32_bf16 v[82:85], v[156:159], v[188:191], v[82:85]
	v_mfma_f32_16x16x32_bf16 v[74:77], v[164:167], v[188:191], v[74:77]
	v_mfma_f32_16x16x32_bf16 v[70:73], v[156:159], v[196:199], v[70:73]
	v_mfma_f32_16x16x32_bf16 v[66:69], v[164:167], v[196:199], v[66:69]
	v_mfma_f32_16x16x32_bf16 v[114:117], v[160:163], v[176:179], v[114:117]
	v_mfma_f32_16x16x32_bf16 v[106:109], v[168:171], v[176:179], v[106:109]
	v_mfma_f32_16x16x32_bf16 v[98:101], v[160:163], v[184:187], v[98:101]
	v_mfma_f32_16x16x32_bf16 v[90:93], v[168:171], v[184:187], v[90:93]
	v_mfma_f32_16x16x32_bf16 v[82:85], v[160:163], v[192:195], v[82:85]
	v_mfma_f32_16x16x32_bf16 v[74:77], v[168:171], v[192:195], v[74:77]
	v_mfma_f32_16x16x32_bf16 v[70:73], v[160:163], v[200:203], v[70:73]
	v_mfma_f32_16x16x32_bf16 v[66:69], v[168:171], v[200:203], v[66:69]
	s_setprio 0
	s_barrier
	ds_read_b128 v[172:175], v138 offset:16384
	ds_read_b128 v[176:179], v138 offset:17408
	ds_read_b128 v[180:183], v138 offset:18432
	ds_read_b128 v[184:187], v138 offset:19456
	ds_read_b128 v[188:191], v138 offset:20480
	ds_read_b128 v[192:195], v138 offset:21504
	ds_read_b128 v[196:199], v138 offset:22528
	ds_read_b128 v[200:203], v138 offset:23552
	s_mov_b32 m0, s29
	s_nop 0
	global_load_lds_dwordx4 v132, s[64:65]
	s_add_u32 s82, s64, 0x80000
	s_mov_b32 m0, s30
	s_nop 0
	global_load_lds_dwordx4 v134, s[64:65]
	s_addc_u32 s83, s65, 0
	s_mov_b32 m0, s33
	s_nop 0
	global_load_lds_dwordx4 v132, s[82:83]
	s_nop 0
	s_mov_b32 m0, s43
	s_nop 0
	global_load_lds_dwordx4 v134, s[82:83]
	s_nop 0
	s_mov_b32 m0, s28
	s_nop 0
	global_load_lds_dwordx4 v1, s[66:67]
	s_nop 0
	s_mov_b32 m0, s50
	s_nop 0
	global_load_lds_dwordx4 v133, s[66:67]
	s_waitcnt vmcnt(8)
	s_waitcnt lgkmcnt(0)
	s_barrier
	s_setprio 1
	v_mfma_f32_16x16x32_bf16 v[62:65], v[140:143], v[172:175], v[62:65]
	v_mfma_f32_16x16x32_bf16 v[58:61], v[148:151], v[172:175], v[58:61]
	v_mfma_f32_16x16x32_bf16 v[54:57], v[140:143], v[180:183], v[54:57]
	v_mfma_f32_16x16x32_bf16 v[46:49], v[148:151], v[180:183], v[46:49]
	v_mfma_f32_16x16x32_bf16 v[38:41], v[140:143], v[188:191], v[38:41]
	v_mfma_f32_16x16x32_bf16 v[30:33], v[148:151], v[188:191], v[30:33]
	v_mfma_f32_16x16x32_bf16 v[22:25], v[140:143], v[196:199], v[22:25]
	v_mfma_f32_16x16x32_bf16 v[14:17], v[148:151], v[196:199], v[14:17]
	v_mfma_f32_16x16x32_bf16 v[62:65], v[144:147], v[176:179], v[62:65]
	v_mfma_f32_16x16x32_bf16 v[58:61], v[152:155], v[176:179], v[58:61]
	v_mfma_f32_16x16x32_bf16 v[54:57], v[144:147], v[184:187], v[54:57]
	v_mfma_f32_16x16x32_bf16 v[46:49], v[152:155], v[184:187], v[46:49]
	v_mfma_f32_16x16x32_bf16 v[38:41], v[144:147], v[192:195], v[38:41]
	v_mfma_f32_16x16x32_bf16 v[30:33], v[152:155], v[192:195], v[30:33]
	v_mfma_f32_16x16x32_bf16 v[22:25], v[144:147], v[200:203], v[22:25]
	v_mfma_f32_16x16x32_bf16 v[14:17], v[152:155], v[200:203], v[14:17]
	v_mfma_f32_16x16x32_bf16 v[50:53], v[156:159], v[172:175], v[50:53]
	v_mfma_f32_16x16x32_bf16 v[42:45], v[164:167], v[172:175], v[42:45]
	v_mfma_f32_16x16x32_bf16 v[34:37], v[156:159], v[180:183], v[34:37]
	v_mfma_f32_16x16x32_bf16 v[26:29], v[164:167], v[180:183], v[26:29]
	v_mfma_f32_16x16x32_bf16 v[18:21], v[156:159], v[188:191], v[18:21]
	v_mfma_f32_16x16x32_bf16 v[10:13], v[164:167], v[188:191], v[10:13]
	v_mfma_f32_16x16x32_bf16 v[6:9], v[156:159], v[196:199], v[6:9]
	v_mfma_f32_16x16x32_bf16 v[2:5], v[164:167], v[196:199], v[2:5]
	v_mfma_f32_16x16x32_bf16 v[50:53], v[160:163], v[176:179], v[50:53]
	v_mfma_f32_16x16x32_bf16 v[42:45], v[168:171], v[176:179], v[42:45]
	v_mfma_f32_16x16x32_bf16 v[34:37], v[160:163], v[184:187], v[34:37]
	v_mfma_f32_16x16x32_bf16 v[26:29], v[168:171], v[184:187], v[26:29]
	v_mfma_f32_16x16x32_bf16 v[18:21], v[160:163], v[192:195], v[18:21]
	v_mfma_f32_16x16x32_bf16 v[10:13], v[168:171], v[192:195], v[10:13]
	v_mfma_f32_16x16x32_bf16 v[6:9], v[160:163], v[200:203], v[6:9]
	v_mfma_f32_16x16x32_bf16 v[2:5], v[168:171], v[200:203], v[2:5]
	s_setprio 0
	s_barrier
; #define PG8_STAGE(bufoff, gbase, voff) do { _Pragma("unroll") for (int _i = 0; _i < 2; ++_i) \
;         pg8_glds((const void*)(gbase), (voff)[_i], (unsigned)__builtin_amdgcn_readfirstlane((int)(lds_u + (unsigned)(bufoff) + ldsw + (unsigned)(_i * 8192)))); } while (0)
; #define PG8_LDA(dst, b, h) do { _Pragma("unroll") for (int m = 0; m < 4; ++m) _Pragma("unroll") for (int k = 0; k < 2; ++k) dst[m][k] = *(const PG8_LAS bf16x8*)(lds + PG8_SA(b, h) + aoff + m * 2048 + k * 1024); } while (0)
; #define PG8_LDB(dst, b, h) do { _Pragma("unroll") for (int n = 0; n < 2; ++n) _Pragma("unroll") for (int k = 0; k < 2; ++k) dst[n][k] = *(const PG8_LAS bf16x8*)(lds + PG8_SB(b, h) + boff + n * 2048 + k * 1024); } while (0)
; #define PG8_MMA(ai, bj, At, Bt) do { __builtin_amdgcn_s_setprio(1); _Pragma("unroll") for (int m = 0; m < 4; ++m) _Pragma("unroll") for (int n = 0; n < 2; ++n) _Pragma("unroll") for (int k = 0; k < 2; ++k) \
;         acc[ai][bj][m][n] = __builtin_amdgcn_mfma_f32_16x16x32_bf16(Bt[n][k], At[m][k], acc[ai][bj][m][n], 0, 0, 0); __builtin_amdgcn_s_setprio(0); } while (0)
; #define PG8_WAIT_V(n) asm volatile("s_waitcnt vmcnt(" #n ")" ::: "memory")
; #define PG8_WAIT_L(n) asm volatile("s_waitcnt lgkmcnt(" #n ")" ::: "memory")
; #define PG8_BAR __builtin_amdgcn_s_barrier()
; #define PG8_SCHED __builtin_amdgcn_sched_barrier(0)
; template <class Epi, class Sched, bool ALIGN_EPI = false, bool SP2 = false>
; __device__ __forceinline__ void gemm_phase(PG8_LAS unsigned char* lds, const Gemm g, const Sched& S, const Epi& E) {
;     ...
;             PG8_LDB(B0, 1, 0); PG8_LDB(B1, 1, 1); PG8_SCHED; PG8_LDA(At, 1, 0); PG8_STAGE(PG8_SA(0, 1), a2 + hstepA, voffA);
;             PG8_WAIT_V(8); PG8_WAIT_L(0); PG8_BAR; PG8_MMA(0, 0, At, B0); PG8_MMA(0, 1, At, B1); PG8_BAR; PG8_SCHED;
;             PG8_LDA(At, 1, 1); PG8_STAGE(PG8_SB(1, 0), b3, voffB); PG8_STAGE(PG8_SB(1, 1), b3 + hstepB, voffB); PG8_STAGE(PG8_SA(1, 0), a3, voffA);
;             PG8_WAIT_V(8); PG8_WAIT_L(0); PG8_BAR; PG8_MMA(1, 0, At, B0); PG8_MMA(1, 1, At, B1); PG8_BAR; PG8_SCHED;
;     ...
;         if constexpr (ALIGN_EPI) { if (wr == 0) PG8_BAR; }
	v_add_u32_e32 v130, 0x18000, v137
	ds_read_b128 v[140:143], v130
	ds_read_b128 v[144:147], v130 offset:1024
	ds_read_b128 v[148:151], v130 offset:2048
	ds_read_b128 v[152:155], v130 offset:3072
	v_add_u32_e32 v130, 0x1c000, v137
	ds_read_b128 v[156:159], v130
	ds_read_b128 v[160:163], v130 offset:1024
	ds_read_b128 v[164:167], v130 offset:2048
	ds_read_b128 v[168:171], v130 offset:3072
	ds_read_b128 v[172:175], v138 offset:32768
	ds_read_b128 v[176:179], v138 offset:33792
	ds_read_b128 v[180:183], v138 offset:34816
	ds_read_b128 v[184:187], v138 offset:35840
	ds_read_b128 v[188:191], v138 offset:36864
	ds_read_b128 v[192:195], v138 offset:37888
	ds_read_b128 v[196:199], v138 offset:38912
	ds_read_b128 v[200:203], v138 offset:39936
	s_add_u32 s66, s66, 0x80000
	s_addc_u32 s67, s67, 0
	s_mov_b32 m0, s51
	s_nop 0
	global_load_lds_dwordx4 v1, s[66:67]
	s_nop 0
	s_mov_b32 m0, s52
	s_nop 0
	global_load_lds_dwordx4 v133, s[66:67]
	s_waitcnt vmcnt(8)
	s_waitcnt lgkmcnt(0)
	s_barrier
	s_setprio 1
	v_mfma_f32_16x16x32_bf16 v[126:129], v[140:143], v[172:175], v[126:129]
	v_mfma_f32_16x16x32_bf16 v[122:125], v[148:151], v[172:175], v[122:125]
	v_mfma_f32_16x16x32_bf16 v[118:121], v[140:143], v[180:183], v[118:121]
	v_mfma_f32_16x16x32_bf16 v[110:113], v[148:151], v[180:183], v[110:113]
	v_mfma_f32_16x16x32_bf16 v[102:105], v[140:143], v[188:191], v[102:105]
	v_mfma_f32_16x16x32_bf16 v[94:97], v[148:151], v[188:191], v[94:97]
	v_mfma_f32_16x16x32_bf16 v[86:89], v[140:143], v[196:199], v[86:89]
	v_mfma_f32_16x16x32_bf16 v[78:81], v[148:151], v[196:199], v[78:81]
	v_mfma_f32_16x16x32_bf16 v[126:129], v[144:147], v[176:179], v[126:129]
	v_mfma_f32_16x16x32_bf16 v[122:125], v[152:155], v[176:179], v[122:125]
	v_mfma_f32_16x16x32_bf16 v[118:121], v[144:147], v[184:187], v[118:121]
	v_mfma_f32_16x16x32_bf16 v[110:113], v[152:155], v[184:187], v[110:113]
	v_mfma_f32_16x16x32_bf16 v[102:105], v[144:147], v[192:195], v[102:105]
	v_mfma_f32_16x16x32_bf16 v[94:97], v[152:155], v[192:195], v[94:97]
	v_mfma_f32_16x16x32_bf16 v[86:89], v[144:147], v[200:203], v[86:89]
	v_mfma_f32_16x16x32_bf16 v[78:81], v[152:155], v[200:203], v[78:81]
	v_mfma_f32_16x16x32_bf16 v[114:117], v[156:159], v[172:175], v[114:117]
	v_mfma_f32_16x16x32_bf16 v[106:109], v[164:167], v[172:175], v[106:109]
	v_mfma_f32_16x16x32_bf16 v[98:101], v[156:159], v[180:183], v[98:101]
	v_mfma_f32_16x16x32_bf16 v[90:93], v[164:167], v[180:183], v[90:93]
	v_mfma_f32_16x16x32_bf16 v[82:85], v[156:159], v[188:191], v[82:85]
	v_mfma_f32_16x16x32_bf16 v[74:77], v[164:167], v[188:191], v[74:77]
	v_mfma_f32_16x16x32_bf16 v[70:73], v[156:159], v[196:199], v[70:73]
	v_mfma_f32_16x16x32_bf16 v[66:69], v[164:167], v[196:199], v[66:69]
	v_mfma_f32_16x16x32_bf16 v[114:117], v[160:163], v[176:179], v[114:117]
	v_mfma_f32_16x16x32_bf16 v[106:109], v[168:171], v[176:179], v[106:109]
	v_mfma_f32_16x16x32_bf16 v[98:101], v[160:163], v[184:187], v[98:101]
	v_mfma_f32_16x16x32_bf16 v[90:93], v[168:171], v[184:187], v[90:93]
	v_mfma_f32_16x16x32_bf16 v[82:85], v[160:163], v[192:195], v[82:85]
	v_mfma_f32_16x16x32_bf16 v[74:77], v[168:171], v[192:195], v[74:77]
	v_mfma_f32_16x16x32_bf16 v[70:73], v[160:163], v[200:203], v[70:73]
	v_mfma_f32_16x16x32_bf16 v[66:69], v[168:171], v[200:203], v[66:69]
	s_setprio 0
	s_barrier
	ds_read_b128 v[172:175], v138 offset:49152
	ds_read_b128 v[176:179], v138 offset:50176
	ds_read_b128 v[180:183], v138 offset:51200
	ds_read_b128 v[184:187], v138 offset:52224
	ds_read_b128 v[188:191], v138 offset:53248
	ds_read_b128 v[192:195], v138 offset:54272
	ds_read_b128 v[196:199], v138 offset:55296
	ds_read_b128 v[200:203], v138 offset:56320
	s_add_u32 s66, s64, 0x80
	s_addc_u32 s67, s65, 0
	s_mov_b32 m0, s53
	s_nop 0
	global_load_lds_dwordx4 v132, s[66:67]
	s_add_u32 s64, s64, 0x80080
	s_mov_b32 m0, s59
	s_nop 0
	global_load_lds_dwordx4 v134, s[66:67]
	s_addc_u32 s65, s65, 0
	s_mov_b32 m0, s70
	s_nop 0
	global_load_lds_dwordx4 v132, s[64:65]
	s_nop 0
	s_mov_b32 m0, s71
	s_nop 0
	global_load_lds_dwordx4 v134, s[64:65]
	s_nop 0
	s_mov_b32 m0, s68
	s_nop 0
	global_load_lds_dwordx4 v1, s[62:63]
	s_nop 0
	s_mov_b32 m0, s69
	s_nop 0
	global_load_lds_dwordx4 v133, s[62:63]
	s_waitcnt vmcnt(8)
	s_waitcnt lgkmcnt(0)
	s_barrier
	s_setprio 1
	v_mfma_f32_16x16x32_bf16 v[62:65], v[140:143], v[172:175], v[62:65]
	v_mfma_f32_16x16x32_bf16 v[58:61], v[148:151], v[172:175], v[58:61]
	v_mfma_f32_16x16x32_bf16 v[54:57], v[140:143], v[180:183], v[54:57]
	v_mfma_f32_16x16x32_bf16 v[46:49], v[148:151], v[180:183], v[46:49]
	v_mfma_f32_16x16x32_bf16 v[38:41], v[140:143], v[188:191], v[38:41]
	v_mfma_f32_16x16x32_bf16 v[30:33], v[148:151], v[188:191], v[30:33]
	v_mfma_f32_16x16x32_bf16 v[22:25], v[140:143], v[196:199], v[22:25]
	v_mfma_f32_16x16x32_bf16 v[14:17], v[148:151], v[196:199], v[14:17]
	v_mfma_f32_16x16x32_bf16 v[62:65], v[144:147], v[176:179], v[62:65]
	v_mfma_f32_16x16x32_bf16 v[58:61], v[152:155], v[176:179], v[58:61]
	v_mfma_f32_16x16x32_bf16 v[54:57], v[144:147], v[184:187], v[54:57]
	v_mfma_f32_16x16x32_bf16 v[46:49], v[152:155], v[184:187], v[46:49]
	v_mfma_f32_16x16x32_bf16 v[38:41], v[144:147], v[192:195], v[38:41]
	v_mfma_f32_16x16x32_bf16 v[30:33], v[152:155], v[192:195], v[30:33]
	v_mfma_f32_16x16x32_bf16 v[22:25], v[144:147], v[200:203], v[22:25]
	v_mfma_f32_16x16x32_bf16 v[14:17], v[152:155], v[200:203], v[14:17]
	v_mfma_f32_16x16x32_bf16 v[50:53], v[156:159], v[172:175], v[50:53]
	v_mfma_f32_16x16x32_bf16 v[42:45], v[164:167], v[172:175], v[42:45]
	v_mfma_f32_16x16x32_bf16 v[34:37], v[156:159], v[180:183], v[34:37]
	v_mfma_f32_16x16x32_bf16 v[26:29], v[164:167], v[180:183], v[26:29]
	v_mfma_f32_16x16x32_bf16 v[18:21], v[156:159], v[188:191], v[18:21]
	v_mfma_f32_16x16x32_bf16 v[10:13], v[164:167], v[188:191], v[10:13]
	v_mfma_f32_16x16x32_bf16 v[6:9], v[156:159], v[196:199], v[6:9]
	v_mfma_f32_16x16x32_bf16 v[2:5], v[164:167], v[196:199], v[2:5]
	v_mfma_f32_16x16x32_bf16 v[50:53], v[160:163], v[176:179], v[50:53]
	v_mfma_f32_16x16x32_bf16 v[42:45], v[168:171], v[176:179], v[42:45]
	v_mfma_f32_16x16x32_bf16 v[34:37], v[160:163], v[184:187], v[34:37]
	v_mfma_f32_16x16x32_bf16 v[26:29], v[168:171], v[184:187], v[26:29]
	v_mfma_f32_16x16x32_bf16 v[18:21], v[160:163], v[192:195], v[18:21]
	v_mfma_f32_16x16x32_bf16 v[10:13], v[168:171], v[192:195], v[10:13]
	v_mfma_f32_16x16x32_bf16 v[6:9], v[160:163], v[200:203], v[6:9]
	v_mfma_f32_16x16x32_bf16 v[2:5], v[168:171], v[200:203], v[2:5]
	s_setprio 0
	s_barrier
	s_add_i32 s81, s81, 2
	s_add_u32 s77, s77, 0x100
	s_addc_u32 s78, s78, 0
	s_add_u32 s79, s79, 0x100
	s_addc_u32 s80, s80, 0
	s_add_u32 s60, s60, 0x100
	s_addc_u32 s61, s61, 0
	s_cmp_gt_u32 s81, 29
	s_cbranch_scc0 .LBB0_507
	s_and_b64 vcc, exec, s[10:11]
	s_cbranch_vccz .LBB0_510
	s_barrier

; #define PG8_STAGE(bufoff, gbase, voff) do { _Pragma("unroll") for (int _i = 0; _i < 2; ++_i) \
;         pg8_glds((const void*)(gbase), (voff)[_i], (unsigned)__builtin_amdgcn_readfirstlane((int)(lds_u + (unsigned)(bufoff) + ldsw + (unsigned)(_i * 8192)))); } while (0)
; #define PG8_LDA(dst, b, h) do { _Pragma("unroll") for (int m = 0; m < 4; ++m) _Pragma("unroll") for (int k = 0; k < 2; ++k) dst[m][k] = *(const PG8_LAS bf16x8*)(lds + PG8_SA(b, h) + aoff + m * 2048 + k * 1024); } while (0)
; #define PG8_LDB(dst, b, h) do { _Pragma("unroll") for (int n = 0; n < 2; ++n) _Pragma("unroll") for (int k = 0; k < 2; ++k) dst[n][k] = *(const PG8_LAS bf16x8*)(lds + PG8_SB(b, h) + boff + n * 2048 + k * 1024); } while (0)
; #define PG8_MMA(ai, bj, At, Bt) do { __builtin_amdgcn_s_setprio(1); _Pragma("unroll") for (int m = 0; m < 4; ++m) _Pragma("unroll") for (int n = 0; n < 2; ++n) _Pragma("unroll") for (int k = 0; k < 2; ++k) \
;         acc[ai][bj][m][n] = __builtin_amdgcn_mfma_f32_16x16x32_bf16(Bt[n][k], At[m][k], acc[ai][bj][m][n], 0, 0, 0); __builtin_amdgcn_s_setprio(0); } while (0)
; #define PG8_WAIT_V(n) asm volatile("s_waitcnt vmcnt(" #n ")" ::: "memory")
; #define PG8_WAIT_L(n) asm volatile("s_waitcnt lgkmcnt(" #n ")" ::: "memory")
; #define PG8_BAR __builtin_amdgcn_s_barrier()
; #define PG8_SCHED __builtin_amdgcn_sched_barrier(0)
; template <class Epi, class Sched, bool ALIGN_EPI = false, bool SP2 = false>
; __device__ __forceinline__ void gemm_phase(PG8_LAS unsigned char* lds, const Gemm g, const Sched& S, const Epi& E) {
;     ...
;             PG8_LDB(B0, 0, 0); PG8_LDB(B1, 0, 1); PG8_SCHED; PG8_LDA(At, 0, 0); PG8_STAGE(PG8_SA(1, 1), a1 + hstepA, voffA);
;             PG8_WAIT_V(8); PG8_WAIT_L(0); PG8_BAR; PG8_MMA(0, 0, At, B0); PG8_MMA(0, 1, At, B1); PG8_BAR; PG8_SCHED;
;             PG8_LDA(At, 0, 1); PG8_STAGE(PG8_SB(0, 0), b2, voffB); PG8_STAGE(PG8_SB(0, 1), b2 + hstepB, voffB); PG8_STAGE(PG8_SA(0, 0), a2, voffA);
;             PG8_WAIT_V(8); PG8_WAIT_L(0); PG8_BAR; PG8_MMA(1, 0, At, B0); PG8_MMA(1, 1, At, B1); PG8_BAR; PG8_SCHED;
.LBB0_680:
	v_add_u32_e32 v134, 0x10000, v171
	v_add_u32_e32 v158, 0x14000, v171
	ds_read_b128 v[122:125], v134
	ds_read_b128 v[126:129], v134 offset:1024
	ds_read_b128 v[130:133], v134 offset:2048
	ds_read_b128 v[134:137], v134 offset:3072
	ds_read_b128 v[146:149], v158
	ds_read_b128 v[150:153], v158 offset:1024
	ds_read_b128 v[154:157], v158 offset:2048
	ds_read_b128 v[158:161], v158 offset:3072
	s_add_u32 s10, s82, 0x100
	s_addc_u32 s11, s83, 0
	s_cmp_eq_u32 s18, 28
	s_cselect_b32 s88, s75, s10
	s_cselect_b32 s89, s13, s11
	s_cselect_b32 s86, vcc_lo, vcc_hi
	s_cselect_b32 s87, s73, s90
	s_add_u32 s84, s88, 0x80
	s_addc_u32 s85, s89, 0
	ds_read_b128 v[162:165], v189
	ds_read_b128 v[166:169], v189 offset:1024
	ds_read_b128 v[176:179], v189 offset:2048
	ds_read_b128 v[180:183], v189 offset:3072
	ds_read_b128 v[192:195], v189 offset:4096
	ds_read_b128 v[196:199], v189 offset:5120
	ds_read_b128 v[200:203], v189 offset:6144
	ds_read_b128 v[204:207], v189 offset:7168
	s_add_u32 s82, s82, 0x80080
	s_addc_u32 s83, s83, 0
	s_mov_b32 m0, s22
	s_nop 0
	global_load_lds_dwordx4 v1, s[82:83]
	s_add_i32 s3, s51, 0xe000
	s_mov_b32 m0, s3
	s_nop 0
	global_load_lds_dwordx4 v186, s[82:83]
	s_waitcnt vmcnt(8)
	s_waitcnt lgkmcnt(0)
	s_barrier
	s_setprio 1
	v_mfma_f32_16x16x32_bf16 v[142:145], v[122:125], v[162:165], v[142:145]
	v_mfma_f32_16x16x32_bf16 v[62:65], v[130:133], v[162:165], v[62:65]
	v_mfma_f32_16x16x32_bf16 v[118:121], v[122:125], v[176:179], v[118:121]
	v_mfma_f32_16x16x32_bf16 v[54:57], v[130:133], v[176:179], v[54:57]
	v_mfma_f32_16x16x32_bf16 v[110:113], v[122:125], v[192:195], v[110:113]
	v_mfma_f32_16x16x32_bf16 v[46:49], v[130:133], v[192:195], v[46:49]
	v_mfma_f32_16x16x32_bf16 v[106:109], v[122:125], v[200:203], v[106:109]
	v_mfma_f32_16x16x32_bf16 v[42:45], v[130:133], v[200:203], v[42:45]
	v_mfma_f32_16x16x32_bf16 v[142:145], v[126:129], v[166:169], v[142:145]
	v_mfma_f32_16x16x32_bf16 v[62:65], v[134:137], v[166:169], v[62:65]
	v_mfma_f32_16x16x32_bf16 v[118:121], v[126:129], v[180:183], v[118:121]
	v_mfma_f32_16x16x32_bf16 v[54:57], v[134:137], v[180:183], v[54:57]
	v_mfma_f32_16x16x32_bf16 v[110:113], v[126:129], v[196:199], v[110:113]
	v_mfma_f32_16x16x32_bf16 v[46:49], v[134:137], v[196:199], v[46:49]
	v_mfma_f32_16x16x32_bf16 v[106:109], v[126:129], v[204:207], v[106:109]
	v_mfma_f32_16x16x32_bf16 v[42:45], v[134:137], v[204:207], v[42:45]
	v_mfma_f32_16x16x32_bf16 v[138:141], v[146:149], v[162:165], v[138:141]
	v_mfma_f32_16x16x32_bf16 v[58:61], v[154:157], v[162:165], v[58:61]
	v_mfma_f32_16x16x32_bf16 v[114:117], v[146:149], v[176:179], v[114:117]
	v_mfma_f32_16x16x32_bf16 v[50:53], v[154:157], v[176:179], v[50:53]
	v_mfma_f32_16x16x32_bf16 v[102:105], v[146:149], v[192:195], v[102:105]
	v_mfma_f32_16x16x32_bf16 v[38:41], v[154:157], v[192:195], v[38:41]
	v_mfma_f32_16x16x32_bf16 v[98:101], v[146:149], v[200:203], v[98:101]
	v_mfma_f32_16x16x32_bf16 v[34:37], v[154:157], v[200:203], v[34:37]
	v_mfma_f32_16x16x32_bf16 v[138:141], v[150:153], v[166:169], v[138:141]
	v_mfma_f32_16x16x32_bf16 v[58:61], v[158:161], v[166:169], v[58:61]
	v_mfma_f32_16x16x32_bf16 v[114:117], v[150:153], v[180:183], v[114:117]
	v_mfma_f32_16x16x32_bf16 v[50:53], v[158:161], v[180:183], v[50:53]
	v_mfma_f32_16x16x32_bf16 v[102:105], v[150:153], v[196:199], v[102:105]
	v_mfma_f32_16x16x32_bf16 v[38:41], v[158:161], v[196:199], v[38:41]
	v_mfma_f32_16x16x32_bf16 v[98:101], v[150:153], v[204:207], v[98:101]
	v_mfma_f32_16x16x32_bf16 v[34:37], v[158:161], v[204:207], v[34:37]
	s_setprio 0
	s_barrier
	ds_read_b128 v[162:165], v189 offset:16384
	ds_read_b128 v[166:169], v189 offset:17408
	ds_read_b128 v[176:179], v189 offset:18432
	ds_read_b128 v[180:183], v189 offset:19456
	ds_read_b128 v[192:195], v189 offset:20480
	ds_read_b128 v[196:199], v189 offset:21504
	ds_read_b128 v[200:203], v189 offset:22528
	ds_read_b128 v[204:207], v189 offset:23552
	s_mov_b32 m0, s81
	s_nop 0
	global_load_lds_dwordx4 v173, s[86:87]
	s_add_u32 s82, s86, 0x80000
	s_mov_b32 m0, s33
	s_nop 0
	global_load_lds_dwordx4 v187, s[86:87]
	s_addc_u32 s83, s87, 0
	s_mov_b32 m0, s91
	s_nop 0
	global_load_lds_dwordx4 v173, s[82:83]
	s_nop 0
	s_mov_b32 m0, s2
	s_nop 0
	global_load_lds_dwordx4 v187, s[82:83]
	s_nop 0
	s_mov_b32 m0, s51
	s_nop 0
	global_load_lds_dwordx4 v1, s[88:89]
	s_nop 0
	s_mov_b32 m0, s52
	s_nop 0
	global_load_lds_dwordx4 v186, s[88:89]
	s_waitcnt vmcnt(8)
	s_waitcnt lgkmcnt(0)
	s_barrier
	s_setprio 1
	v_mfma_f32_16x16x32_bf16 v[94:97], v[122:125], v[162:165], v[94:97]
	v_mfma_f32_16x16x32_bf16 v[30:33], v[130:133], v[162:165], v[30:33]
	v_mfma_f32_16x16x32_bf16 v[86:89], v[122:125], v[176:179], v[86:89]
	v_mfma_f32_16x16x32_bf16 v[22:25], v[130:133], v[176:179], v[22:25]
	v_mfma_f32_16x16x32_bf16 v[78:81], v[122:125], v[192:195], v[78:81]
	v_mfma_f32_16x16x32_bf16 v[14:17], v[130:133], v[192:195], v[14:17]
	v_mfma_f32_16x16x32_bf16 v[74:77], v[122:125], v[200:203], v[74:77]
	v_mfma_f32_16x16x32_bf16 v[10:13], v[130:133], v[200:203], v[10:13]
	v_mfma_f32_16x16x32_bf16 v[94:97], v[126:129], v[166:169], v[94:97]
	v_mfma_f32_16x16x32_bf16 v[30:33], v[134:137], v[166:169], v[30:33]
	v_mfma_f32_16x16x32_bf16 v[86:89], v[126:129], v[180:183], v[86:89]
	v_mfma_f32_16x16x32_bf16 v[22:25], v[134:137], v[180:183], v[22:25]
	v_mfma_f32_16x16x32_bf16 v[78:81], v[126:129], v[196:199], v[78:81]
	v_mfma_f32_16x16x32_bf16 v[14:17], v[134:137], v[196:199], v[14:17]
	v_mfma_f32_16x16x32_bf16 v[74:77], v[126:129], v[204:207], v[74:77]
	v_mfma_f32_16x16x32_bf16 v[10:13], v[134:137], v[204:207], v[10:13]
	v_mfma_f32_16x16x32_bf16 v[90:93], v[146:149], v[162:165], v[90:93]
	v_mfma_f32_16x16x32_bf16 v[26:29], v[154:157], v[162:165], v[26:29]
	v_mfma_f32_16x16x32_bf16 v[82:85], v[146:149], v[176:179], v[82:85]
	v_mfma_f32_16x16x32_bf16 v[18:21], v[154:157], v[176:179], v[18:21]
	v_mfma_f32_16x16x32_bf16 v[70:73], v[146:149], v[192:195], v[70:73]
	v_mfma_f32_16x16x32_bf16 v[6:9], v[154:157], v[192:195], v[6:9]
	v_mfma_f32_16x16x32_bf16 v[66:69], v[146:149], v[200:203], v[66:69]
	v_mfma_f32_16x16x32_bf16 v[2:5], v[154:157], v[200:203], v[2:5]
	v_mfma_f32_16x16x32_bf16 v[90:93], v[150:153], v[166:169], v[90:93]
	v_mfma_f32_16x16x32_bf16 v[26:29], v[158:161], v[166:169], v[26:29]
	v_mfma_f32_16x16x32_bf16 v[82:85], v[150:153], v[180:183], v[82:85]
	v_mfma_f32_16x16x32_bf16 v[18:21], v[158:161], v[180:183], v[18:21]
	v_mfma_f32_16x16x32_bf16 v[70:73], v[150:153], v[196:199], v[70:73]
	v_mfma_f32_16x16x32_bf16 v[6:9], v[158:161], v[196:199], v[6:9]
	v_mfma_f32_16x16x32_bf16 v[66:69], v[150:153], v[204:207], v[66:69]
	v_mfma_f32_16x16x32_bf16 v[2:5], v[158:161], v[204:207], v[2:5]
	s_setprio 0
	s_barrier
; #define PG8_STAGE(bufoff, gbase, voff) do { _Pragma("unroll") for (int _i = 0; _i < 2; ++_i) \
;         pg8_glds((const void*)(gbase), (voff)[_i], (unsigned)__builtin_amdgcn_readfirstlane((int)(lds_u + (unsigned)(bufoff) + ldsw + (unsigned)(_i * 8192)))); } while (0)
; #define PG8_LDA(dst, b, h) do { _Pragma("unroll") for (int m = 0; m < 4; ++m) _Pragma("unroll") for (int k = 0; k < 2; ++k) dst[m][k] = *(const PG8_LAS bf16x8*)(lds + PG8_SA(b, h) + aoff + m * 2048 + k * 1024); } while (0)
; #define PG8_LDB(dst, b, h) do { _Pragma("unroll") for (int n = 0; n < 2; ++n) _Pragma("unroll") for (int k = 0; k < 2; ++k) dst[n][k] = *(const PG8_LAS bf16x8*)(lds + PG8_SB(b, h) + boff + n * 2048 + k * 1024); } while (0)
; #define PG8_MMA(ai, bj, At, Bt) do { __builtin_amdgcn_s_setprio(1); _Pragma("unroll") for (int m = 0; m < 4; ++m) _Pragma("unroll") for (int n = 0; n < 2; ++n) _Pragma("unroll") for (int k = 0; k < 2; ++k) \
;         acc[ai][bj][m][n] = __builtin_amdgcn_mfma_f32_16x16x32_bf16(Bt[n][k], At[m][k], acc[ai][bj][m][n], 0, 0, 0); __builtin_amdgcn_s_setprio(0); } while (0)
; #define PG8_WAIT_V(n) asm volatile("s_waitcnt vmcnt(" #n ")" ::: "memory")
; #define PG8_WAIT_L(n) asm volatile("s_waitcnt lgkmcnt(" #n ")" ::: "memory")
; #define PG8_BAR __builtin_amdgcn_s_barrier()
; #define PG8_SCHED __builtin_amdgcn_sched_barrier(0)
; template <class Epi, class Sched, bool ALIGN_EPI = false, bool SP2 = false>
; __device__ __forceinline__ void gemm_phase(PG8_LAS unsigned char* lds, const Gemm g, const Sched& S, const Epi& E) {
;     ...
;             PG8_LDB(B0, 1, 0); PG8_LDB(B1, 1, 1); PG8_SCHED; PG8_LDA(At, 1, 0); PG8_STAGE(PG8_SA(0, 1), a2 + hstepA, voffA);
;             PG8_WAIT_V(8); PG8_WAIT_L(0); PG8_BAR; PG8_MMA(0, 0, At, B0); PG8_MMA(0, 1, At, B1); PG8_BAR; PG8_SCHED;
;             PG8_LDA(At, 1, 1); PG8_STAGE(PG8_SB(1, 0), b3, voffB); PG8_STAGE(PG8_SB(1, 1), b3 + hstepB, voffB); PG8_STAGE(PG8_SA(1, 0), a3, voffA);
;             PG8_WAIT_V(8); PG8_WAIT_L(0); PG8_BAR; PG8_MMA(1, 0, At, B0); PG8_MMA(1, 1, At, B1); PG8_BAR; PG8_SCHED;
;     ...
;         if constexpr (ALIGN_EPI) { if (wr == 0) PG8_BAR; }
;         if constexpr (!Epi::AFTER_DRAIN) { E(acc, cur, wr, wc, fr, fq, lds + STAGE_BYTES); S.done(cur); }
	v_add_u32_e32 v134, 0x18000, v171
	v_add_u32_e32 v158, 0x1c000, v171
	ds_read_b128 v[122:125], v134
	ds_read_b128 v[126:129], v134 offset:1024
	ds_read_b128 v[130:133], v134 offset:2048
	ds_read_b128 v[134:137], v134 offset:3072
	ds_read_b128 v[146:149], v158
	ds_read_b128 v[150:153], v158 offset:1024
	ds_read_b128 v[154:157], v158 offset:2048
	ds_read_b128 v[158:161], v158 offset:3072
	ds_read_b128 v[162:165], v189 offset:32768
	ds_read_b128 v[166:169], v189 offset:33792
	ds_read_b128 v[176:179], v189 offset:34816
	ds_read_b128 v[180:183], v189 offset:35840
	ds_read_b128 v[192:195], v189 offset:36864
	ds_read_b128 v[196:199], v189 offset:37888
	ds_read_b128 v[200:203], v189 offset:38912
	ds_read_b128 v[204:207], v189 offset:39936
	s_add_u32 s82, s88, 0x80000
	s_addc_u32 s83, s89, 0
	s_mov_b32 m0, s53
	s_nop 0
	global_load_lds_dwordx4 v1, s[82:83]
	s_nop 0
	s_mov_b32 m0, s30
	s_nop 0
	global_load_lds_dwordx4 v186, s[82:83]
	s_waitcnt vmcnt(8)
	s_waitcnt lgkmcnt(0)
	s_barrier
	s_setprio 1
	v_mfma_f32_16x16x32_bf16 v[142:145], v[122:125], v[162:165], v[142:145]
	v_mfma_f32_16x16x32_bf16 v[62:65], v[130:133], v[162:165], v[62:65]
	v_mfma_f32_16x16x32_bf16 v[118:121], v[122:125], v[176:179], v[118:121]
	v_mfma_f32_16x16x32_bf16 v[54:57], v[130:133], v[176:179], v[54:57]
	v_mfma_f32_16x16x32_bf16 v[110:113], v[122:125], v[192:195], v[110:113]
	v_mfma_f32_16x16x32_bf16 v[46:49], v[130:133], v[192:195], v[46:49]
	v_mfma_f32_16x16x32_bf16 v[106:109], v[122:125], v[200:203], v[106:109]
	v_mfma_f32_16x16x32_bf16 v[42:45], v[130:133], v[200:203], v[42:45]
	v_mfma_f32_16x16x32_bf16 v[142:145], v[126:129], v[166:169], v[142:145]
	v_mfma_f32_16x16x32_bf16 v[62:65], v[134:137], v[166:169], v[62:65]
	v_mfma_f32_16x16x32_bf16 v[118:121], v[126:129], v[180:183], v[118:121]
	v_mfma_f32_16x16x32_bf16 v[54:57], v[134:137], v[180:183], v[54:57]
	v_mfma_f32_16x16x32_bf16 v[110:113], v[126:129], v[196:199], v[110:113]
	v_mfma_f32_16x16x32_bf16 v[46:49], v[134:137], v[196:199], v[46:49]
	v_mfma_f32_16x16x32_bf16 v[106:109], v[126:129], v[204:207], v[106:109]
	v_mfma_f32_16x16x32_bf16 v[42:45], v[134:137], v[204:207], v[42:45]
	v_mfma_f32_16x16x32_bf16 v[138:141], v[146:149], v[162:165], v[138:141]
	v_mfma_f32_16x16x32_bf16 v[58:61], v[154:157], v[162:165], v[58:61]
	v_mfma_f32_16x16x32_bf16 v[114:117], v[146:149], v[176:179], v[114:117]
	v_mfma_f32_16x16x32_bf16 v[50:53], v[154:157], v[176:179], v[50:53]
	v_mfma_f32_16x16x32_bf16 v[102:105], v[146:149], v[192:195], v[102:105]
	v_mfma_f32_16x16x32_bf16 v[38:41], v[154:157], v[192:195], v[38:41]
	v_mfma_f32_16x16x32_bf16 v[98:101], v[146:149], v[200:203], v[98:101]
	v_mfma_f32_16x16x32_bf16 v[34:37], v[154:157], v[200:203], v[34:37]
	v_mfma_f32_16x16x32_bf16 v[138:141], v[150:153], v[166:169], v[138:141]
	v_mfma_f32_16x16x32_bf16 v[58:61], v[158:161], v[166:169], v[58:61]
	v_mfma_f32_16x16x32_bf16 v[114:117], v[150:153], v[180:183], v[114:117]
	v_mfma_f32_16x16x32_bf16 v[50:53], v[158:161], v[180:183], v[50:53]
	v_mfma_f32_16x16x32_bf16 v[102:105], v[150:153], v[196:199], v[102:105]
	v_mfma_f32_16x16x32_bf16 v[38:41], v[158:161], v[196:199], v[38:41]
	v_mfma_f32_16x16x32_bf16 v[98:101], v[150:153], v[204:207], v[98:101]
	v_mfma_f32_16x16x32_bf16 v[34:37], v[158:161], v[204:207], v[34:37]
	s_setprio 0
	s_barrier
	ds_read_b128 v[162:165], v189 offset:49152
	ds_read_b128 v[166:169], v189 offset:50176
	ds_read_b128 v[176:179], v189 offset:51200
	ds_read_b128 v[180:183], v189 offset:52224
	ds_read_b128 v[192:195], v189 offset:53248
	ds_read_b128 v[196:199], v189 offset:54272
	ds_read_b128 v[200:203], v189 offset:55296
	ds_read_b128 v[204:207], v189 offset:56320
	s_add_u32 s82, s86, 0x80
	s_addc_u32 s83, s87, 0
	s_mov_b32 m0, s97
	s_nop 0
	global_load_lds_dwordx4 v173, s[82:83]
	s_nop 0
	s_mov_b32 m0, s94
	s_nop 0
	global_load_lds_dwordx4 v187, s[82:83]
	s_add_u32 s82, s86, 0x80080
	s_addc_u32 s83, s87, 0
	s_mov_b32 m0, s28
	s_nop 0
	global_load_lds_dwordx4 v173, s[82:83]
	s_nop 0
	s_mov_b32 m0, s29
	s_nop 0
	global_load_lds_dwordx4 v187, s[82:83]
	s_nop 0
	s_mov_b32 m0, s95
	s_nop 0
	global_load_lds_dwordx4 v1, s[84:85]
	s_nop 0
	s_mov_b32 m0, s0
	s_nop 0
	global_load_lds_dwordx4 v186, s[84:85]
	s_waitcnt vmcnt(8)
	s_waitcnt lgkmcnt(0)
	s_barrier
	s_setprio 1
	v_mfma_f32_16x16x32_bf16 v[94:97], v[122:125], v[162:165], v[94:97]
	v_mfma_f32_16x16x32_bf16 v[30:33], v[130:133], v[162:165], v[30:33]
	v_mfma_f32_16x16x32_bf16 v[86:89], v[122:125], v[176:179], v[86:89]
	v_mfma_f32_16x16x32_bf16 v[22:25], v[130:133], v[176:179], v[22:25]
	v_mfma_f32_16x16x32_bf16 v[78:81], v[122:125], v[192:195], v[78:81]
	v_mfma_f32_16x16x32_bf16 v[14:17], v[130:133], v[192:195], v[14:17]
	v_mfma_f32_16x16x32_bf16 v[74:77], v[122:125], v[200:203], v[74:77]
	v_mfma_f32_16x16x32_bf16 v[10:13], v[130:133], v[200:203], v[10:13]
	v_mfma_f32_16x16x32_bf16 v[94:97], v[126:129], v[166:169], v[94:97]
	v_mfma_f32_16x16x32_bf16 v[30:33], v[134:137], v[166:169], v[30:33]
	v_mfma_f32_16x16x32_bf16 v[86:89], v[126:129], v[180:183], v[86:89]
	v_mfma_f32_16x16x32_bf16 v[22:25], v[134:137], v[180:183], v[22:25]
	v_mfma_f32_16x16x32_bf16 v[78:81], v[126:129], v[196:199], v[78:81]
	v_mfma_f32_16x16x32_bf16 v[14:17], v[134:137], v[196:199], v[14:17]
	v_mfma_f32_16x16x32_bf16 v[74:77], v[126:129], v[204:207], v[74:77]
	v_mfma_f32_16x16x32_bf16 v[10:13], v[134:137], v[204:207], v[10:13]
	v_mfma_f32_16x16x32_bf16 v[90:93], v[146:149], v[162:165], v[90:93]
	v_mfma_f32_16x16x32_bf16 v[26:29], v[154:157], v[162:165], v[26:29]
	v_mfma_f32_16x16x32_bf16 v[82:85], v[146:149], v[176:179], v[82:85]
	v_mfma_f32_16x16x32_bf16 v[18:21], v[154:157], v[176:179], v[18:21]
	v_mfma_f32_16x16x32_bf16 v[70:73], v[146:149], v[192:195], v[70:73]
	v_mfma_f32_16x16x32_bf16 v[6:9], v[154:157], v[192:195], v[6:9]
	v_mfma_f32_16x16x32_bf16 v[66:69], v[146:149], v[200:203], v[66:69]
	v_mfma_f32_16x16x32_bf16 v[2:5], v[154:157], v[200:203], v[2:5]
	v_mfma_f32_16x16x32_bf16 v[90:93], v[150:153], v[166:169], v[90:93]
	v_mfma_f32_16x16x32_bf16 v[26:29], v[158:161], v[166:169], v[26:29]
	v_mfma_f32_16x16x32_bf16 v[82:85], v[150:153], v[180:183], v[82:85]
	v_mfma_f32_16x16x32_bf16 v[18:21], v[158:161], v[180:183], v[18:21]
	v_mfma_f32_16x16x32_bf16 v[70:73], v[150:153], v[196:199], v[70:73]
	v_mfma_f32_16x16x32_bf16 v[6:9], v[158:161], v[196:199], v[6:9]
	v_mfma_f32_16x16x32_bf16 v[66:69], v[150:153], v[204:207], v[66:69]
	v_mfma_f32_16x16x32_bf16 v[2:5], v[158:161], v[204:207], v[2:5]
	s_setprio 0
	s_barrier
	s_add_i32 s18, s18, 2
	s_add_u32 vcc_hi, vcc_hi, 0x100
	s_addc_u32 s90, s90, 0
	s_cmp_gt_u32 s18, 29
	s_mov_b64 s[82:83], s[10:11]
	s_cbranch_scc0 .LBB0_680
	s_and_b64 vcc, exec, s[62:63]
	s_cbranch_vccnz .LBB0_705
	s_and_saveexec_b64 s[10:11], s[6:7]
	s_cbranch_execnz .LBB0_706

; #define PG8_STAGE(bufoff, gbase, voff) do { _Pragma("unroll") for (int _i = 0; _i < 2; ++_i) \
;         pg8_glds((const void*)(gbase), (voff)[_i], (unsigned)__builtin_amdgcn_readfirstlane((int)(lds_u + (unsigned)(bufoff) + ldsw + (unsigned)(_i * 8192)))); } while (0)
; #define PG8_LDA(dst, b, h) do { _Pragma("unroll") for (int m = 0; m < 4; ++m) _Pragma("unroll") for (int k = 0; k < 2; ++k) dst[m][k] = *(const PG8_LAS bf16x8*)(lds + PG8_SA(b, h) + aoff + m * 2048 + k * 1024); } while (0)
; #define PG8_LDB(dst, b, h) do { _Pragma("unroll") for (int n = 0; n < 2; ++n) _Pragma("unroll") for (int k = 0; k < 2; ++k) dst[n][k] = *(const PG8_LAS bf16x8*)(lds + PG8_SB(b, h) + boff + n * 2048 + k * 1024); } while (0)
; #define PG8_MMA(ai, bj, At, Bt) do { __builtin_amdgcn_s_setprio(1); _Pragma("unroll") for (int m = 0; m < 4; ++m) _Pragma("unroll") for (int n = 0; n < 2; ++n) _Pragma("unroll") for (int k = 0; k < 2; ++k) \
;         acc[ai][bj][m][n] = __builtin_amdgcn_mfma_f32_16x16x32_bf16(Bt[n][k], At[m][k], acc[ai][bj][m][n], 0, 0, 0); __builtin_amdgcn_s_setprio(0); } while (0)
; #define PG8_WAIT_V(n) asm volatile("s_waitcnt vmcnt(" #n ")" ::: "memory")
; #define PG8_BAR __builtin_amdgcn_s_barrier()
; template <class Epi, class Sched, bool ALIGN_EPI = false, bool SP2 = false>
; __device__ __forceinline__ void gemm_phase(PG8_LAS unsigned char* lds, const Gemm g, const Sched& S, const Epi& E) {
;     ...
;         for (int t = 0; t < nt; t += 2) {
;             const bool last = (t == nt - 2);
;             const char* a1 = cA + (size_t)(t + 1) * kstep;
;             const char* a2 = last ? nA : cA + (size_t)(t + 2) * kstep; const char* b2 = last ? nB : cB + (size_t)(t + 2) * kstep;
;             const char* a3 = a2 + kstep; const char* b3 = b2 + kstep;
;             if (last && has_next) S.a_ready(nxt);
;             if constexpr (SP2) {
;             PG8_LDB(B0, 0, 0); PG8_LDB(B1, 0, 1); PG8_SCHED; PG8_LDA(At, 0, 0); PG8_STAGE(PG8_SA(1, 1), a1 + hstepA, voffA);
;             PG8_WAIT_V(8); PG8_WAIT_L(0); PG8_BAR; PG8_MMA(0, 0, At, B0); PG8_MMA(0, 1, At, B1); PG8_BAR; PG8_SCHED;
;             PG8_LDA(At, 0, 1); PG8_STAGE(PG8_SB(0, 0), b2, voffB); PG8_STAGE(PG8_SB(0, 1), b2 + hstepB, voffB); PG8_STAGE(PG8_SA(0, 0), a2, voffA);
;             PG8_WAIT_V(8); PG8_WAIT_L(0); PG8_BAR; PG8_MMA(1, 0, At, B0); PG8_MMA(1, 1, At, B1); PG8_BAR; PG8_SCHED;
.LBB0_841:
	v_add_u32_e32 v130, 0x10000, v137
	ds_read_b128 v[140:143], v130
	ds_read_b128 v[144:147], v130 offset:1024
	ds_read_b128 v[148:151], v130 offset:2048
	ds_read_b128 v[152:155], v130 offset:3072
	v_add_u32_e32 v130, 0x14000, v137
	ds_read_b128 v[156:159], v130
	ds_read_b128 v[160:163], v130 offset:1024
	ds_read_b128 v[164:167], v130 offset:2048
	ds_read_b128 v[168:171], v130 offset:3072
	s_cmpk_eq_i32 s77, 0x54
	s_cselect_b32 s60, s6, s73
	s_cselect_b32 s61, s7, s74
	s_cselect_b32 s58, s16, s75
	s_cselect_b32 s59, s17, s76
	s_add_u32 s56, s60, 0x80
	s_addc_u32 s57, s61, 0
	ds_read_b128 v[172:175], v138
	ds_read_b128 v[176:179], v138 offset:1024
	ds_read_b128 v[180:183], v138 offset:2048
	ds_read_b128 v[184:187], v138 offset:3072
	ds_read_b128 v[188:191], v138 offset:4096
	ds_read_b128 v[192:195], v138 offset:5120
	ds_read_b128 v[196:199], v138 offset:6144
	ds_read_b128 v[200:203], v138 offset:7168
	s_mov_b32 m0, s67
	s_nop 0
	global_load_lds_dwordx4 v1, s[54:55]
	s_add_i32 s3, s28, 0xe000
	s_mov_b32 m0, s3
	s_nop 0
	global_load_lds_dwordx4 v133, s[54:55]
	s_waitcnt vmcnt(8)
	s_waitcnt lgkmcnt(0)
	s_barrier
	s_setprio 1
	v_mfma_f32_16x16x32_bf16 v[126:129], v[140:143], v[172:175], v[126:129]
	v_mfma_f32_16x16x32_bf16 v[122:125], v[148:151], v[172:175], v[122:125]
	v_mfma_f32_16x16x32_bf16 v[118:121], v[140:143], v[180:183], v[118:121]
	v_mfma_f32_16x16x32_bf16 v[110:113], v[148:151], v[180:183], v[110:113]
	v_mfma_f32_16x16x32_bf16 v[102:105], v[140:143], v[188:191], v[102:105]
	v_mfma_f32_16x16x32_bf16 v[94:97], v[148:151], v[188:191], v[94:97]
	v_mfma_f32_16x16x32_bf16 v[86:89], v[140:143], v[196:199], v[86:89]
	v_mfma_f32_16x16x32_bf16 v[78:81], v[148:151], v[196:199], v[78:81]
	v_mfma_f32_16x16x32_bf16 v[126:129], v[144:147], v[176:179], v[126:129]
	v_mfma_f32_16x16x32_bf16 v[122:125], v[152:155], v[176:179], v[122:125]
	v_mfma_f32_16x16x32_bf16 v[118:121], v[144:147], v[184:187], v[118:121]
	v_mfma_f32_16x16x32_bf16 v[110:113], v[152:155], v[184:187], v[110:113]
	v_mfma_f32_16x16x32_bf16 v[102:105], v[144:147], v[192:195], v[102:105]
	v_mfma_f32_16x16x32_bf16 v[94:97], v[152:155], v[192:195], v[94:97]
	v_mfma_f32_16x16x32_bf16 v[86:89], v[144:147], v[200:203], v[86:89]
	v_mfma_f32_16x16x32_bf16 v[78:81], v[152:155], v[200:203], v[78:81]
	v_mfma_f32_16x16x32_bf16 v[114:117], v[156:159], v[172:175], v[114:117]
	v_mfma_f32_16x16x32_bf16 v[106:109], v[164:167], v[172:175], v[106:109]
	v_mfma_f32_16x16x32_bf16 v[98:101], v[156:159], v[180:183], v[98:101]
	v_mfma_f32_16x16x32_bf16 v[90:93], v[164:167], v[180:183], v[90:93]
	v_mfma_f32_16x16x32_bf16 v[82:85], v[156:159], v[188:191], v[82:85]
	v_mfma_f32_16x16x32_bf16 v[74:77], v[164:167], v[188:191], v[74:77]
	v_mfma_f32_16x16x32_bf16 v[70:73], v[156:159], v[196:199], v[70:73]
	v_mfma_f32_16x16x32_bf16 v[66:69], v[164:167], v[196:199], v[66:69]
	v_mfma_f32_16x16x32_bf16 v[114:117], v[160:163], v[176:179], v[114:117]
	v_mfma_f32_16x16x32_bf16 v[106:109], v[168:171], v[176:179], v[106:109]
	v_mfma_f32_16x16x32_bf16 v[98:101], v[160:163], v[184:187], v[98:101]
	v_mfma_f32_16x16x32_bf16 v[90:93], v[168:171], v[184:187], v[90:93]
	v_mfma_f32_16x16x32_bf16 v[82:85], v[160:163], v[192:195], v[82:85]
	v_mfma_f32_16x16x32_bf16 v[74:77], v[168:171], v[192:195], v[74:77]
	v_mfma_f32_16x16x32_bf16 v[70:73], v[160:163], v[200:203], v[70:73]
	v_mfma_f32_16x16x32_bf16 v[66:69], v[168:171], v[200:203], v[66:69]
	s_setprio 0
	s_barrier
	ds_read_b128 v[172:175], v138 offset:16384
	ds_read_b128 v[176:179], v138 offset:17408
	ds_read_b128 v[180:183], v138 offset:18432
	ds_read_b128 v[184:187], v138 offset:19456
	ds_read_b128 v[188:191], v138 offset:20480
	ds_read_b128 v[192:195], v138 offset:21504
	ds_read_b128 v[196:199], v138 offset:22528
	ds_read_b128 v[200:203], v138 offset:23552
	s_mov_b32 m0, s29
	s_nop 0
	global_load_lds_dwordx4 v132, s[58:59]
	s_add_u32 s78, s58, 0x160000
	s_mov_b32 m0, s30
	s_nop 0
	global_load_lds_dwordx4 v134, s[58:59]
	s_addc_u32 s79, s59, 0
	s_mov_b32 m0, s33
	s_nop 0
	global_load_lds_dwordx4 v132, s[78:79]
	s_nop 0
	s_mov_b32 m0, s43
	s_nop 0
	global_load_lds_dwordx4 v134, s[78:79]
	s_nop 0
	s_mov_b32 m0, s28
	s_nop 0
	global_load_lds_dwordx4 v1, s[60:61]
	s_nop 0
	s_mov_b32 m0, s50
	s_nop 0
	global_load_lds_dwordx4 v133, s[60:61]
	s_waitcnt vmcnt(8)
	s_waitcnt lgkmcnt(0)
	s_barrier
	s_setprio 1
	v_mfma_f32_16x16x32_bf16 v[62:65], v[140:143], v[172:175], v[62:65]
	v_mfma_f32_16x16x32_bf16 v[58:61], v[148:151], v[172:175], v[58:61]
	v_mfma_f32_16x16x32_bf16 v[54:57], v[140:143], v[180:183], v[54:57]
	v_mfma_f32_16x16x32_bf16 v[46:49], v[148:151], v[180:183], v[46:49]
	v_mfma_f32_16x16x32_bf16 v[38:41], v[140:143], v[188:191], v[38:41]
	v_mfma_f32_16x16x32_bf16 v[30:33], v[148:151], v[188:191], v[30:33]
	v_mfma_f32_16x16x32_bf16 v[22:25], v[140:143], v[196:199], v[22:25]
	v_mfma_f32_16x16x32_bf16 v[14:17], v[148:151], v[196:199], v[14:17]
	v_mfma_f32_16x16x32_bf16 v[62:65], v[144:147], v[176:179], v[62:65]
	v_mfma_f32_16x16x32_bf16 v[58:61], v[152:155], v[176:179], v[58:61]
	v_mfma_f32_16x16x32_bf16 v[54:57], v[144:147], v[184:187], v[54:57]
	v_mfma_f32_16x16x32_bf16 v[46:49], v[152:155], v[184:187], v[46:49]
	v_mfma_f32_16x16x32_bf16 v[38:41], v[144:147], v[192:195], v[38:41]
	v_mfma_f32_16x16x32_bf16 v[30:33], v[152:155], v[192:195], v[30:33]
	v_mfma_f32_16x16x32_bf16 v[22:25], v[144:147], v[200:203], v[22:25]
	v_mfma_f32_16x16x32_bf16 v[14:17], v[152:155], v[200:203], v[14:17]
	v_mfma_f32_16x16x32_bf16 v[50:53], v[156:159], v[172:175], v[50:53]
	v_mfma_f32_16x16x32_bf16 v[42:45], v[164:167], v[172:175], v[42:45]
	v_mfma_f32_16x16x32_bf16 v[34:37], v[156:159], v[180:183], v[34:37]
	v_mfma_f32_16x16x32_bf16 v[26:29], v[164:167], v[180:183], v[26:29]
	v_mfma_f32_16x16x32_bf16 v[18:21], v[156:159], v[188:191], v[18:21]
	v_mfma_f32_16x16x32_bf16 v[10:13], v[164:167], v[188:191], v[10:13]
	v_mfma_f32_16x16x32_bf16 v[6:9], v[156:159], v[196:199], v[6:9]
	v_mfma_f32_16x16x32_bf16 v[2:5], v[164:167], v[196:199], v[2:5]
	v_mfma_f32_16x16x32_bf16 v[50:53], v[160:163], v[176:179], v[50:53]
	v_mfma_f32_16x16x32_bf16 v[42:45], v[168:171], v[176:179], v[42:45]
	v_mfma_f32_16x16x32_bf16 v[34:37], v[160:163], v[184:187], v[34:37]
	v_mfma_f32_16x16x32_bf16 v[26:29], v[168:171], v[184:187], v[26:29]
	v_mfma_f32_16x16x32_bf16 v[18:21], v[160:163], v[192:195], v[18:21]
	v_mfma_f32_16x16x32_bf16 v[10:13], v[168:171], v[192:195], v[10:13]
	v_mfma_f32_16x16x32_bf16 v[6:9], v[160:163], v[200:203], v[6:9]
	v_mfma_f32_16x16x32_bf16 v[2:5], v[168:171], v[200:203], v[2:5]
	s_setprio 0
	s_barrier
; #define PG8_STAGE(bufoff, gbase, voff) do { _Pragma("unroll") for (int _i = 0; _i < 2; ++_i) \
;         pg8_glds((const void*)(gbase), (voff)[_i], (unsigned)__builtin_amdgcn_readfirstlane((int)(lds_u + (unsigned)(bufoff) + ldsw + (unsigned)(_i * 8192)))); } while (0)
; #define PG8_LDA(dst, b, h) do { _Pragma("unroll") for (int m = 0; m < 4; ++m) _Pragma("unroll") for (int k = 0; k < 2; ++k) dst[m][k] = *(const PG8_LAS bf16x8*)(lds + PG8_SA(b, h) + aoff + m * 2048 + k * 1024); } while (0)
; #define PG8_LDB(dst, b, h) do { _Pragma("unroll") for (int n = 0; n < 2; ++n) _Pragma("unroll") for (int k = 0; k < 2; ++k) dst[n][k] = *(const PG8_LAS bf16x8*)(lds + PG8_SB(b, h) + boff + n * 2048 + k * 1024); } while (0)
; #define PG8_MMA(ai, bj, At, Bt) do { __builtin_amdgcn_s_setprio(1); _Pragma("unroll") for (int m = 0; m < 4; ++m) _Pragma("unroll") for (int n = 0; n < 2; ++n) _Pragma("unroll") for (int k = 0; k < 2; ++k) \
;         acc[ai][bj][m][n] = __builtin_amdgcn_mfma_f32_16x16x32_bf16(Bt[n][k], At[m][k], acc[ai][bj][m][n], 0, 0, 0); __builtin_amdgcn_s_setprio(0); } while (0)
; #define PG8_WAIT_V(n) asm volatile("s_waitcnt vmcnt(" #n ")" ::: "memory")
; #define PG8_WAIT_L(n) asm volatile("s_waitcnt lgkmcnt(" #n ")" ::: "memory")
; #define PG8_BAR __builtin_amdgcn_s_barrier()
; #define PG8_SCHED __builtin_amdgcn_sched_barrier(0)
; template <class Epi, class Sched, bool ALIGN_EPI = false, bool SP2 = false>
; __device__ __forceinline__ void gemm_phase(PG8_LAS unsigned char* lds, const Gemm g, const Sched& S, const Epi& E) {
;     ...
;         for (int t = 0; t < nt; t += 2) {
;     ...
;             PG8_LDB(B0, 1, 0); PG8_LDB(B1, 1, 1); PG8_SCHED; PG8_LDA(At, 1, 0); PG8_STAGE(PG8_SA(0, 1), a2 + hstepA, voffA);
;             PG8_WAIT_V(8); PG8_WAIT_L(0); PG8_BAR; PG8_MMA(0, 0, At, B0); PG8_MMA(0, 1, At, B1); PG8_BAR; PG8_SCHED;
;             PG8_LDA(At, 1, 1); PG8_STAGE(PG8_SB(1, 0), b3, voffB); PG8_STAGE(PG8_SB(1, 1), b3 + hstepB, voffB); PG8_STAGE(PG8_SA(1, 0), a3, voffA);
;             PG8_WAIT_V(8); PG8_WAIT_L(0); PG8_BAR; PG8_MMA(1, 0, At, B0); PG8_MMA(1, 1, At, B1); PG8_BAR; PG8_SCHED;
	v_add_u32_e32 v130, 0x18000, v137
	ds_read_b128 v[140:143], v130
	ds_read_b128 v[144:147], v130 offset:1024
	ds_read_b128 v[148:151], v130 offset:2048
	ds_read_b128 v[152:155], v130 offset:3072
	v_add_u32_e32 v130, 0x1c000, v137
	ds_read_b128 v[156:159], v130
	ds_read_b128 v[160:163], v130 offset:1024
	ds_read_b128 v[164:167], v130 offset:2048
	ds_read_b128 v[168:171], v130 offset:3072
	ds_read_b128 v[172:175], v138 offset:32768
	ds_read_b128 v[176:179], v138 offset:33792
	ds_read_b128 v[180:183], v138 offset:34816
	ds_read_b128 v[184:187], v138 offset:35840
	ds_read_b128 v[188:191], v138 offset:36864
	ds_read_b128 v[192:195], v138 offset:37888
	ds_read_b128 v[196:199], v138 offset:38912
	ds_read_b128 v[200:203], v138 offset:39936
	s_add_u32 s60, s60, 0x160000
	s_addc_u32 s61, s61, 0
	s_mov_b32 m0, s51
	s_nop 0
	global_load_lds_dwordx4 v1, s[60:61]
	s_nop 0
	s_mov_b32 m0, s52
	s_nop 0
	global_load_lds_dwordx4 v133, s[60:61]
	s_waitcnt vmcnt(8)
	s_waitcnt lgkmcnt(0)
	s_barrier
	s_setprio 1
	v_mfma_f32_16x16x32_bf16 v[126:129], v[140:143], v[172:175], v[126:129]
	v_mfma_f32_16x16x32_bf16 v[122:125], v[148:151], v[172:175], v[122:125]
	v_mfma_f32_16x16x32_bf16 v[118:121], v[140:143], v[180:183], v[118:121]
	v_mfma_f32_16x16x32_bf16 v[110:113], v[148:151], v[180:183], v[110:113]
	v_mfma_f32_16x16x32_bf16 v[102:105], v[140:143], v[188:191], v[102:105]
	v_mfma_f32_16x16x32_bf16 v[94:97], v[148:151], v[188:191], v[94:97]
	v_mfma_f32_16x16x32_bf16 v[86:89], v[140:143], v[196:199], v[86:89]
	v_mfma_f32_16x16x32_bf16 v[78:81], v[148:151], v[196:199], v[78:81]
	v_mfma_f32_16x16x32_bf16 v[126:129], v[144:147], v[176:179], v[126:129]
	v_mfma_f32_16x16x32_bf16 v[122:125], v[152:155], v[176:179], v[122:125]
	v_mfma_f32_16x16x32_bf16 v[118:121], v[144:147], v[184:187], v[118:121]
	v_mfma_f32_16x16x32_bf16 v[110:113], v[152:155], v[184:187], v[110:113]
	v_mfma_f32_16x16x32_bf16 v[102:105], v[144:147], v[192:195], v[102:105]
	v_mfma_f32_16x16x32_bf16 v[94:97], v[152:155], v[192:195], v[94:97]
	v_mfma_f32_16x16x32_bf16 v[86:89], v[144:147], v[200:203], v[86:89]
	v_mfma_f32_16x16x32_bf16 v[78:81], v[152:155], v[200:203], v[78:81]
	v_mfma_f32_16x16x32_bf16 v[114:117], v[156:159], v[172:175], v[114:117]
	v_mfma_f32_16x16x32_bf16 v[106:109], v[164:167], v[172:175], v[106:109]
	v_mfma_f32_16x16x32_bf16 v[98:101], v[156:159], v[180:183], v[98:101]
	v_mfma_f32_16x16x32_bf16 v[90:93], v[164:167], v[180:183], v[90:93]
	v_mfma_f32_16x16x32_bf16 v[82:85], v[156:159], v[188:191], v[82:85]
	v_mfma_f32_16x16x32_bf16 v[74:77], v[164:167], v[188:191], v[74:77]
	v_mfma_f32_16x16x32_bf16 v[70:73], v[156:159], v[196:199], v[70:73]
	v_mfma_f32_16x16x32_bf16 v[66:69], v[164:167], v[196:199], v[66:69]
	v_mfma_f32_16x16x32_bf16 v[114:117], v[160:163], v[176:179], v[114:117]
	v_mfma_f32_16x16x32_bf16 v[106:109], v[168:171], v[176:179], v[106:109]
	v_mfma_f32_16x16x32_bf16 v[98:101], v[160:163], v[184:187], v[98:101]
	v_mfma_f32_16x16x32_bf16 v[90:93], v[168:171], v[184:187], v[90:93]
	v_mfma_f32_16x16x32_bf16 v[82:85], v[160:163], v[192:195], v[82:85]
	v_mfma_f32_16x16x32_bf16 v[74:77], v[168:171], v[192:195], v[74:77]
	v_mfma_f32_16x16x32_bf16 v[70:73], v[160:163], v[200:203], v[70:73]
	v_mfma_f32_16x16x32_bf16 v[66:69], v[168:171], v[200:203], v[66:69]
	s_setprio 0
	s_barrier
	ds_read_b128 v[172:175], v138 offset:49152
	ds_read_b128 v[176:179], v138 offset:50176
	ds_read_b128 v[180:183], v138 offset:51200
	ds_read_b128 v[184:187], v138 offset:52224
	ds_read_b128 v[188:191], v138 offset:53248
	ds_read_b128 v[192:195], v138 offset:54272
	ds_read_b128 v[196:199], v138 offset:55296
	ds_read_b128 v[200:203], v138 offset:56320
	s_add_u32 s60, s58, 0x80
	s_addc_u32 s61, s59, 0
	s_mov_b32 m0, s53
	s_nop 0
	global_load_lds_dwordx4 v132, s[60:61]
	s_add_u32 s58, s58, 0x160080
	s_mov_b32 m0, s62
	s_nop 0
	global_load_lds_dwordx4 v134, s[60:61]
	s_addc_u32 s59, s59, 0
	s_mov_b32 m0, s65
	s_nop 0
	global_load_lds_dwordx4 v132, s[58:59]
	s_nop 0
	s_mov_b32 m0, s66
	s_nop 0
	global_load_lds_dwordx4 v134, s[58:59]
	s_nop 0
	s_mov_b32 m0, s63
	s_nop 0
	global_load_lds_dwordx4 v1, s[56:57]
	s_nop 0
	s_mov_b32 m0, s64
	s_nop 0
	global_load_lds_dwordx4 v133, s[56:57]
	s_waitcnt vmcnt(8)
	s_waitcnt lgkmcnt(0)
	s_barrier
	s_setprio 1
	v_mfma_f32_16x16x32_bf16 v[62:65], v[140:143], v[172:175], v[62:65]
	v_mfma_f32_16x16x32_bf16 v[58:61], v[148:151], v[172:175], v[58:61]
	v_mfma_f32_16x16x32_bf16 v[54:57], v[140:143], v[180:183], v[54:57]
	v_mfma_f32_16x16x32_bf16 v[46:49], v[148:151], v[180:183], v[46:49]
	v_mfma_f32_16x16x32_bf16 v[38:41], v[140:143], v[188:191], v[38:41]
	v_mfma_f32_16x16x32_bf16 v[30:33], v[148:151], v[188:191], v[30:33]
	v_mfma_f32_16x16x32_bf16 v[22:25], v[140:143], v[196:199], v[22:25]
	v_mfma_f32_16x16x32_bf16 v[14:17], v[148:151], v[196:199], v[14:17]
	v_mfma_f32_16x16x32_bf16 v[62:65], v[144:147], v[176:179], v[62:65]
	v_mfma_f32_16x16x32_bf16 v[58:61], v[152:155], v[176:179], v[58:61]
	v_mfma_f32_16x16x32_bf16 v[54:57], v[144:147], v[184:187], v[54:57]
	v_mfma_f32_16x16x32_bf16 v[46:49], v[152:155], v[184:187], v[46:49]
	v_mfma_f32_16x16x32_bf16 v[38:41], v[144:147], v[192:195], v[38:41]
	v_mfma_f32_16x16x32_bf16 v[30:33], v[152:155], v[192:195], v[30:33]
	v_mfma_f32_16x16x32_bf16 v[22:25], v[144:147], v[200:203], v[22:25]
	v_mfma_f32_16x16x32_bf16 v[14:17], v[152:155], v[200:203], v[14:17]
	v_mfma_f32_16x16x32_bf16 v[50:53], v[156:159], v[172:175], v[50:53]
	v_mfma_f32_16x16x32_bf16 v[42:45], v[164:167], v[172:175], v[42:45]
	v_mfma_f32_16x16x32_bf16 v[34:37], v[156:159], v[180:183], v[34:37]
	v_mfma_f32_16x16x32_bf16 v[26:29], v[164:167], v[180:183], v[26:29]
	v_mfma_f32_16x16x32_bf16 v[18:21], v[156:159], v[188:191], v[18:21]
	v_mfma_f32_16x16x32_bf16 v[10:13], v[164:167], v[188:191], v[10:13]
	v_mfma_f32_16x16x32_bf16 v[6:9], v[156:159], v[196:199], v[6:9]
	v_mfma_f32_16x16x32_bf16 v[2:5], v[164:167], v[196:199], v[2:5]
	v_mfma_f32_16x16x32_bf16 v[50:53], v[160:163], v[176:179], v[50:53]
	v_mfma_f32_16x16x32_bf16 v[42:45], v[168:171], v[176:179], v[42:45]
	v_mfma_f32_16x16x32_bf16 v[34:37], v[160:163], v[184:187], v[34:37]
	v_mfma_f32_16x16x32_bf16 v[26:29], v[168:171], v[184:187], v[26:29]
	v_mfma_f32_16x16x32_bf16 v[18:21], v[160:163], v[192:195], v[18:21]
	v_mfma_f32_16x16x32_bf16 v[10:13], v[168:171], v[192:195], v[10:13]
	v_mfma_f32_16x16x32_bf16 v[6:9], v[160:163], v[200:203], v[6:9]
	v_mfma_f32_16x16x32_bf16 v[2:5], v[168:171], v[200:203], v[2:5]
	s_setprio 0
	s_barrier
	s_add_i32 s77, s77, 2
	s_add_u32 s73, s73, 0x100
	s_addc_u32 s74, s74, 0
	s_add_u32 s75, s75, 0x100
	s_addc_u32 s76, s76, 0
	s_add_u32 s54, s54, 0x100
	s_addc_u32 s55, s55, 0
	s_cmpk_gt_u32 s77, 0x55
	s_cbranch_scc0 .LBB0_841
	s_and_b64 vcc, exec, s[12:13]
	s_cbranch_vccz .LBB0_844
	s_barrier
